# diff-attn: per-stage and per-tile alternating wave priority, asm-pad nops removed from bias chains; QKV result stores write-through
# speedup vs baseline: 1.0150x; 1.0150x over previous
.LBB0_106:
	s_add_u32 s3, s4, 0xfffe0080
	s_addc_u32 s14, s5, -1
	s_cmp_eq_u32 s42, 4
	s_cselect_b32 s17, s7, s14
	s_cselect_b32 s16, s38, s3
	s_cselect_b32 s15, s9, s41
	s_cselect_b32 s14, s39, s40
	s_add_i32 s3, 0, 0x14000
	v_add_u32_e32 v92, s93, v182
	v_add_u32_e32 v124, s3, v182
	ds_read_b128 v[60:63], v92
	ds_read_b128 v[68:71], v92 offset:1024
	ds_read_b128 v[88:91], v92 offset:2048
	ds_read_b128 v[92:95], v92 offset:3072
	ds_read_b128 v[104:107], v124
	ds_read_b128 v[108:111], v124 offset:1024
	ds_read_b128 v[116:119], v124 offset:2048
	ds_read_b128 v[124:127], v124 offset:3072
	s_add_i32 m0, s23, 0xc000
	ds_read_b128 v[166:169], v183
	ds_read_b128 v[170:173], v183 offset:1024
	ds_read_b128 v[174:177], v183 offset:2048
	ds_read_b128 v[178:181], v183 offset:3072
	ds_read_b128 v[184:187], v183 offset:4096
	ds_read_b128 v[188:191], v183 offset:5120
	ds_read_b128 v[192:195], v183 offset:6144
	ds_read_b128 v[196:199], v183 offset:7168
	global_load_lds_dwordx4 v230, s[4:5]
	s_add_i32 m0, s23, 0xe000
	v_mov_b32_e32 v163, v231
	global_load_lds_dwordx4 v162, s[4:5]
	s_waitcnt vmcnt(8)
	s_waitcnt lgkmcnt(0)
	s_barrier
	s_setprio 1
	s_waitcnt lgkmcnt(0)
	v_mfma_i32_16x16x64_i8 v[156:159], v[60:63], v[166:169], v[156:159]
	v_mfma_i32_16x16x64_i8 v[152:155], v[88:91], v[166:169], v[152:155]
	v_mfma_i32_16x16x64_i8 v[140:143], v[60:63], v[174:177], v[140:143]
	v_mfma_i32_16x16x64_i8 v[136:139], v[88:91], v[174:177], v[136:139]
	v_mfma_i32_16x16x64_i8 v[120:123], v[60:63], v[184:187], v[120:123]
	v_mfma_i32_16x16x64_i8 v[112:115], v[88:91], v[184:187], v[112:115]
	v_mfma_i32_16x16x64_i8 v[84:87], v[60:63], v[192:195], v[84:87]
	v_mfma_i32_16x16x64_i8 v[80:83], v[88:91], v[192:195], v[80:83]
	v_mfma_i32_16x16x64_i8 v[156:159], v[68:71], v[170:173], v[156:159]
	v_mfma_i32_16x16x64_i8 v[152:155], v[92:95], v[170:173], v[152:155]
	v_mfma_i32_16x16x64_i8 v[140:143], v[68:71], v[178:181], v[140:143]
	v_mfma_i32_16x16x64_i8 v[136:139], v[92:95], v[178:181], v[136:139]
	v_mfma_i32_16x16x64_i8 v[120:123], v[68:71], v[188:191], v[120:123]
	v_mfma_i32_16x16x64_i8 v[112:115], v[92:95], v[188:191], v[112:115]
	v_mfma_i32_16x16x64_i8 v[84:87], v[68:71], v[196:199], v[84:87]
	v_mfma_i32_16x16x64_i8 v[80:83], v[92:95], v[196:199], v[80:83]
	s_setprio 0
	s_setprio 1
	v_mfma_i32_16x16x64_i8 v[148:151], v[104:107], v[166:169], v[148:151]
	v_mfma_i32_16x16x64_i8 v[144:147], v[116:119], v[166:169], v[144:147]
	v_mfma_i32_16x16x64_i8 v[132:135], v[104:107], v[174:177], v[132:135]
	v_mfma_i32_16x16x64_i8 v[128:131], v[116:119], v[174:177], v[128:131]
	v_mfma_i32_16x16x64_i8 v[100:103], v[104:107], v[184:187], v[100:103]
	v_mfma_i32_16x16x64_i8 v[96:99], v[116:119], v[184:187], v[96:99]
	v_mfma_i32_16x16x64_i8 v[76:79], v[104:107], v[192:195], v[76:79]
	v_mfma_i32_16x16x64_i8 v[72:75], v[116:119], v[192:195], v[72:75]
	v_mfma_i32_16x16x64_i8 v[148:151], v[108:111], v[170:173], v[148:151]
	v_mfma_i32_16x16x64_i8 v[144:147], v[124:127], v[170:173], v[144:147]
	v_mfma_i32_16x16x64_i8 v[132:135], v[108:111], v[178:181], v[132:135]
	v_mfma_i32_16x16x64_i8 v[128:131], v[124:127], v[178:181], v[128:131]
	v_mfma_i32_16x16x64_i8 v[100:103], v[108:111], v[188:191], v[100:103]
	v_mfma_i32_16x16x64_i8 v[96:99], v[124:127], v[188:191], v[96:99]
	v_mfma_i32_16x16x64_i8 v[76:79], v[108:111], v[196:199], v[76:79]
	v_mfma_i32_16x16x64_i8 v[72:75], v[124:127], v[196:199], v[72:75]
	s_setprio 0
	s_barrier
	s_add_i32 s43, s93, s22
	s_mov_b32 m0, s43
	ds_read_b128 v[166:169], v183 offset:16384
	ds_read_b128 v[170:173], v183 offset:17408
	ds_read_b128 v[174:177], v183 offset:18432
	ds_read_b128 v[178:181], v183 offset:19456
	ds_read_b128 v[184:187], v183 offset:20480
	ds_read_b128 v[188:191], v183 offset:21504
	ds_read_b128 v[192:195], v183 offset:22528
	ds_read_b128 v[196:199], v183 offset:23552
	global_load_lds_dwordx4 v160, s[14:15]
	s_add_i32 m0, s43, 0x2000
	s_add_u32 s44, s14, 0x20000
	s_addc_u32 s45, s15, 0
	s_add_i32 s3, s3, s22
	global_load_lds_dwordx4 v164, s[14:15]
	s_mov_b32 m0, s3
	v_mov_b32_e32 v161, v231
	global_load_lds_dwordx4 v160, s[44:45]
	s_add_i32 m0, s3, 0x2000
	v_mov_b32_e32 v165, v231
	global_load_lds_dwordx4 v164, s[44:45]
	s_mov_b32 m0, s23
	v_lshl_add_u64 v[200:201], s[14:15], 0, v[160:161]
	global_load_lds_dwordx4 v230, s[16:17]
	s_mov_b32 m0, s24
	v_lshl_add_u64 v[202:203], s[14:15], 0, v[164:165]
	global_load_lds_dwordx4 v162, s[16:17]
	s_waitcnt vmcnt(8)
	s_waitcnt lgkmcnt(0)
	v_lshl_add_u64 v[204:205], s[16:17], 0, v[230:231]
	v_lshl_add_u64 v[206:207], s[16:17], 0, v[162:163]
	s_barrier
	s_setprio 1
	s_waitcnt lgkmcnt(0)
	v_mfma_i32_16x16x64_i8 v[64:67], v[60:63], v[166:169], v[64:67]
	v_mfma_i32_16x16x64_i8 v[56:59], v[88:91], v[166:169], v[56:59]
	v_mfma_i32_16x16x64_i8 v[44:47], v[60:63], v[174:177], v[44:47]
	v_mfma_i32_16x16x64_i8 v[40:43], v[88:91], v[174:177], v[40:43]
	v_mfma_i32_16x16x64_i8 v[28:31], v[60:63], v[184:187], v[28:31]
	v_mfma_i32_16x16x64_i8 v[24:27], v[88:91], v[184:187], v[24:27]
	v_mfma_i32_16x16x64_i8 v[12:15], v[60:63], v[192:195], v[12:15]
	v_mfma_i32_16x16x64_i8 v[8:11], v[88:91], v[192:195], v[8:11]
	v_mfma_i32_16x16x64_i8 v[64:67], v[68:71], v[170:173], v[64:67]
	v_mfma_i32_16x16x64_i8 v[56:59], v[92:95], v[170:173], v[56:59]
	v_mfma_i32_16x16x64_i8 v[44:47], v[68:71], v[178:181], v[44:47]
	v_mfma_i32_16x16x64_i8 v[40:43], v[92:95], v[178:181], v[40:43]
	v_mfma_i32_16x16x64_i8 v[28:31], v[68:71], v[188:191], v[28:31]
	v_mfma_i32_16x16x64_i8 v[24:27], v[92:95], v[188:191], v[24:27]
	v_mfma_i32_16x16x64_i8 v[12:15], v[68:71], v[196:199], v[12:15]
	v_mfma_i32_16x16x64_i8 v[8:11], v[92:95], v[196:199], v[8:11]
	s_setprio 0
	s_setprio 1
	v_mfma_i32_16x16x64_i8 v[52:55], v[104:107], v[166:169], v[52:55]
	v_mfma_i32_16x16x64_i8 v[48:51], v[116:119], v[166:169], v[48:51]
	v_mfma_i32_16x16x64_i8 v[36:39], v[104:107], v[174:177], v[36:39]
	v_mfma_i32_16x16x64_i8 v[32:35], v[116:119], v[174:177], v[32:35]
	v_mfma_i32_16x16x64_i8 v[20:23], v[104:107], v[184:187], v[20:23]
	v_mfma_i32_16x16x64_i8 v[16:19], v[116:119], v[184:187], v[16:19]
	v_mfma_i32_16x16x64_i8 v[4:7], v[104:107], v[192:195], v[4:7]
	v_mfma_i32_16x16x64_i8 v[0:3], v[116:119], v[192:195], v[0:3]
	v_mfma_i32_16x16x64_i8 v[52:55], v[108:111], v[170:173], v[52:55]
	v_mfma_i32_16x16x64_i8 v[48:51], v[124:127], v[170:173], v[48:51]
	v_mfma_i32_16x16x64_i8 v[36:39], v[108:111], v[178:181], v[36:39]
	v_mfma_i32_16x16x64_i8 v[32:35], v[124:127], v[178:181], v[32:35]
	v_mfma_i32_16x16x64_i8 v[20:23], v[108:111], v[188:191], v[20:23]
	v_mfma_i32_16x16x64_i8 v[16:19], v[124:127], v[188:191], v[16:19]
	v_mfma_i32_16x16x64_i8 v[4:7], v[108:111], v[196:199], v[4:7]
	v_mfma_i32_16x16x64_i8 v[0:3], v[124:127], v[196:199], v[0:3]
	s_setprio 0
	s_barrier
	s_add_i32 s3, 0, 0x1c000
	v_add_u32_e32 v92, s2, v182
	v_add_u32_e32 v124, s3, v182
	ds_read_b128 v[60:63], v92
	ds_read_b128 v[68:71], v92 offset:1024
	ds_read_b128 v[88:91], v92 offset:2048
	ds_read_b128 v[92:95], v92 offset:3072
	ds_read_b128 v[104:107], v124
	ds_read_b128 v[108:111], v124 offset:1024
	ds_read_b128 v[116:119], v124 offset:2048
	ds_read_b128 v[124:127], v124 offset:3072
	s_add_u32 s16, s16, 0x20000
	s_addc_u32 s17, s17, 0
	s_mov_b32 m0, s25
	ds_read_b128 v[166:169], v183 offset:32768
	ds_read_b128 v[170:173], v183 offset:33792
	ds_read_b128 v[174:177], v183 offset:34816
	ds_read_b128 v[178:181], v183 offset:35840
	ds_read_b128 v[184:187], v183 offset:36864
	ds_read_b128 v[188:191], v183 offset:37888
	ds_read_b128 v[192:195], v183 offset:38912
	ds_read_b128 v[196:199], v183 offset:39936
	global_load_lds_dwordx4 v230, s[16:17]
	s_mov_b32 m0, s26
	s_nop 0
	global_load_lds_dwordx4 v162, s[16:17]
	s_waitcnt vmcnt(8)
	s_waitcnt lgkmcnt(0)
	s_barrier
	s_setprio 1
	s_waitcnt lgkmcnt(0)
	v_mfma_i32_16x16x64_i8 v[156:159], v[60:63], v[166:169], v[156:159]
	v_mfma_i32_16x16x64_i8 v[152:155], v[88:91], v[166:169], v[152:155]
	v_mfma_i32_16x16x64_i8 v[140:143], v[60:63], v[174:177], v[140:143]
	v_mfma_i32_16x16x64_i8 v[136:139], v[88:91], v[174:177], v[136:139]
	v_mfma_i32_16x16x64_i8 v[120:123], v[60:63], v[184:187], v[120:123]
	v_mfma_i32_16x16x64_i8 v[112:115], v[88:91], v[184:187], v[112:115]
	v_mfma_i32_16x16x64_i8 v[84:87], v[60:63], v[192:195], v[84:87]
	v_mfma_i32_16x16x64_i8 v[80:83], v[88:91], v[192:195], v[80:83]
	v_mfma_i32_16x16x64_i8 v[156:159], v[68:71], v[170:173], v[156:159]
	v_mfma_i32_16x16x64_i8 v[152:155], v[92:95], v[170:173], v[152:155]
	v_mfma_i32_16x16x64_i8 v[140:143], v[68:71], v[178:181], v[140:143]
	v_mfma_i32_16x16x64_i8 v[136:139], v[92:95], v[178:181], v[136:139]
	v_mfma_i32_16x16x64_i8 v[120:123], v[68:71], v[188:191], v[120:123]
	v_mfma_i32_16x16x64_i8 v[112:115], v[92:95], v[188:191], v[112:115]
	v_mfma_i32_16x16x64_i8 v[84:87], v[68:71], v[196:199], v[84:87]
	v_mfma_i32_16x16x64_i8 v[80:83], v[92:95], v[196:199], v[80:83]
	s_setprio 0
	s_setprio 1
	v_mfma_i32_16x16x64_i8 v[148:151], v[104:107], v[166:169], v[148:151]
	v_mfma_i32_16x16x64_i8 v[144:147], v[116:119], v[166:169], v[144:147]
	v_mfma_i32_16x16x64_i8 v[132:135], v[104:107], v[174:177], v[132:135]
	v_mfma_i32_16x16x64_i8 v[128:131], v[116:119], v[174:177], v[128:131]
	v_mfma_i32_16x16x64_i8 v[100:103], v[104:107], v[184:187], v[100:103]
	v_mfma_i32_16x16x64_i8 v[96:99], v[116:119], v[184:187], v[96:99]
	v_mfma_i32_16x16x64_i8 v[76:79], v[104:107], v[192:195], v[76:79]
	v_mfma_i32_16x16x64_i8 v[72:75], v[116:119], v[192:195], v[72:75]
	v_mfma_i32_16x16x64_i8 v[148:151], v[108:111], v[170:173], v[148:151]
	v_mfma_i32_16x16x64_i8 v[144:147], v[124:127], v[170:173], v[144:147]
	v_mfma_i32_16x16x64_i8 v[132:135], v[108:111], v[178:181], v[132:135]
	v_mfma_i32_16x16x64_i8 v[128:131], v[124:127], v[178:181], v[128:131]
	v_mfma_i32_16x16x64_i8 v[100:103], v[108:111], v[188:191], v[100:103]
	v_mfma_i32_16x16x64_i8 v[96:99], v[124:127], v[188:191], v[96:99]
	v_mfma_i32_16x16x64_i8 v[76:79], v[108:111], v[196:199], v[76:79]
	v_mfma_i32_16x16x64_i8 v[72:75], v[124:127], v[196:199], v[72:75]
	s_setprio 0
	s_barrier
	s_add_i32 s16, s2, s22
	v_lshl_add_u64 v[200:201], v[200:201], 0, s[96:97]
	s_mov_b32 m0, s16
	ds_read_b128 v[166:169], v183 offset:49152
	ds_read_b128 v[170:173], v183 offset:50176
	ds_read_b128 v[174:177], v183 offset:51200
	ds_read_b128 v[178:181], v183 offset:52224
	ds_read_b128 v[184:187], v183 offset:53248
	ds_read_b128 v[188:191], v183 offset:54272
	ds_read_b128 v[192:195], v183 offset:55296
	ds_read_b128 v[196:199], v183 offset:56320
	global_load_lds_dwordx4 v[200:201], off
	s_add_i32 m0, s16, 0x2000
	s_add_u32 s14, s14, 0x20080
	v_lshl_add_u64 v[200:201], v[202:203], 0, s[96:97]
	s_addc_u32 s15, s15, 0
	s_add_i32 s3, s3, s22
	global_load_lds_dwordx4 v[200:201], off
	s_mov_b32 m0, s3
	v_lshl_add_u64 v[200:201], v[204:205], 0, s[96:97]
	global_load_lds_dwordx4 v160, s[14:15]
	s_add_i32 m0, s3, 0x2000
	s_nop 0
	global_load_lds_dwordx4 v164, s[14:15]
	s_mov_b32 m0, s31
	s_nop 0
	global_load_lds_dwordx4 v[200:201], off
	v_lshl_add_u64 v[200:201], v[206:207], 0, s[96:97]
	s_mov_b32 m0, s33
	s_nop 0
	global_load_lds_dwordx4 v[200:201], off
	s_waitcnt vmcnt(8)
	s_waitcnt lgkmcnt(0)
	s_barrier
	s_setprio 1
	s_waitcnt lgkmcnt(0)
	v_mfma_i32_16x16x64_i8 v[64:67], v[60:63], v[166:169], v[64:67]
	v_mfma_i32_16x16x64_i8 v[56:59], v[88:91], v[166:169], v[56:59]
	v_mfma_i32_16x16x64_i8 v[44:47], v[60:63], v[174:177], v[44:47]
	v_mfma_i32_16x16x64_i8 v[40:43], v[88:91], v[174:177], v[40:43]
	v_mfma_i32_16x16x64_i8 v[28:31], v[60:63], v[184:187], v[28:31]
	v_mfma_i32_16x16x64_i8 v[24:27], v[88:91], v[184:187], v[24:27]
	v_mfma_i32_16x16x64_i8 v[12:15], v[60:63], v[192:195], v[12:15]
	v_mfma_i32_16x16x64_i8 v[8:11], v[88:91], v[192:195], v[8:11]
	v_mfma_i32_16x16x64_i8 v[64:67], v[68:71], v[170:173], v[64:67]
	v_mfma_i32_16x16x64_i8 v[56:59], v[92:95], v[170:173], v[56:59]
	v_mfma_i32_16x16x64_i8 v[44:47], v[68:71], v[178:181], v[44:47]
	v_mfma_i32_16x16x64_i8 v[40:43], v[92:95], v[178:181], v[40:43]
	v_mfma_i32_16x16x64_i8 v[28:31], v[68:71], v[188:191], v[28:31]
	v_mfma_i32_16x16x64_i8 v[24:27], v[92:95], v[188:191], v[24:27]
	v_mfma_i32_16x16x64_i8 v[12:15], v[68:71], v[196:199], v[12:15]
	v_mfma_i32_16x16x64_i8 v[8:11], v[92:95], v[196:199], v[8:11]
	s_setprio 0
	s_setprio 1
	v_mfma_i32_16x16x64_i8 v[52:55], v[104:107], v[166:169], v[52:55]
	v_mfma_i32_16x16x64_i8 v[48:51], v[116:119], v[166:169], v[48:51]
	v_mfma_i32_16x16x64_i8 v[36:39], v[104:107], v[174:177], v[36:39]
	v_mfma_i32_16x16x64_i8 v[32:35], v[116:119], v[174:177], v[32:35]
	v_mfma_i32_16x16x64_i8 v[20:23], v[104:107], v[184:187], v[20:23]
	v_mfma_i32_16x16x64_i8 v[16:19], v[116:119], v[184:187], v[16:19]
	v_mfma_i32_16x16x64_i8 v[4:7], v[104:107], v[192:195], v[4:7]
	v_mfma_i32_16x16x64_i8 v[0:3], v[116:119], v[192:195], v[0:3]
	v_mfma_i32_16x16x64_i8 v[52:55], v[108:111], v[170:173], v[52:55]
	v_mfma_i32_16x16x64_i8 v[48:51], v[124:127], v[170:173], v[48:51]
	v_mfma_i32_16x16x64_i8 v[36:39], v[108:111], v[178:181], v[36:39]
	v_mfma_i32_16x16x64_i8 v[32:35], v[124:127], v[178:181], v[32:35]
	v_mfma_i32_16x16x64_i8 v[20:23], v[108:111], v[188:191], v[20:23]
	v_mfma_i32_16x16x64_i8 v[16:19], v[124:127], v[188:191], v[16:19]
	v_mfma_i32_16x16x64_i8 v[4:7], v[108:111], v[196:199], v[4:7]
	v_mfma_i32_16x16x64_i8 v[0:3], v[124:127], v[196:199], v[0:3]
	s_setprio 0
	s_barrier
	s_add_i32 s42, s42, 2
	s_add_u32 s4, s4, 0x100
	s_addc_u32 s5, s5, 0
	s_add_u32 s40, s40, 0x100
	s_addc_u32 s41, s41, 0
	s_cmp_gt_u32 s42, 5
	s_cbranch_scc0 .LBB0_106
	s_ashr_i32 s4, s36, 31
	s_lshr_b32 s4, s4, 30
	s_add_i32 s4, s36, s4
	s_mul_i32 s3, s37, 0xc00
	s_ashr_i32 s4, s4, 2
	s_add_i32 s3, s3, 0
	s_ashr_i32 s5, s4, 31
	s_add_i32 s3, s3, 0x20340
	s_lshl_b32 s7, s36, 8
	s_lshl_b32 s9, s4, 10
	s_lshl_b64 s[4:5], s[4:5], 25
	v_mbcnt_lo_u32_b32 v60, -1, 0
	v_mbcnt_hi_u32_b32 v60, -1, v60
	s_add_u32 s4, s64, s4
	v_and_b32_e32 v161, 15, v60
	v_ashrrev_i32_e32 v163, 4, v60
	s_addc_u32 s5, s65, s5
	v_lshl_add_u32 v124, v163, 3, s28
	s_sub_i32 s7, s7, s9
	v_lshl_add_u32 v126, v124, 2, s3
	v_add_u32_e32 v124, s7, v124
	v_add_u32_e32 v168, s27, v161
	v_ashrrev_i32_e32 v125, 31, v124
	ds_read_b128 v[104:107], v126 offset:16
	ds_read_b128 v[88:91], v126 offset:512
	ds_read_b128 v[108:111], v126 offset:1040
	ds_read_b128 v[68:71], v126 offset:1536
	ds_read_b128 v[116:119], v126 offset:1024
	ds_read_b128 v[92:95], v126 offset:528
	ds_read_b128 v[60:63], v126 offset:1552
	v_lshl_add_u64 v[166:167], v[124:125], 1, s[4:5]
	v_lshl_add_u32 v165, v168, 2, s3
	ds_read_b128 v[124:127], v126
	ds_read_b32 v174, v165 offset:2048
	v_cvt_f32_i32_e32 v171, v158
	v_cvt_f32_i32_e32 v170, v156
	v_cvt_f32_i32_e32 v179, v159
	v_cvt_f32_i32_e32 v178, v157
	s_waitcnt lgkmcnt(0)
	v_mov_b32_e32 v156, v116
	v_pk_mul_f32 v[176:177], v[174:175], v[170:171] op_sel_hi:[0,1]
	v_mov_b32_e32 v170, v124
	v_mov_b32_e32 v171, v126
	v_mov_b32_e32 v157, v118
	v_pk_fma_f32 v[158:159], v[176:177], v[170:171], v[156:157]
	v_pk_mul_f32 v[176:177], v[174:175], v[178:179] op_sel_hi:[0,1]
	v_cvt_f32_i32_e32 v179, v152
	v_cvt_f32_i32_e32 v178, v154
	v_cvt_f32_i32_e32 v181, v153
	v_cvt_f32_i32_e32 v180, v155
	v_lshl_add_u32 v168, s35, 8, v168
	s_and_b32 s4, s36, -4
	v_ashrrev_i32_e32 v169, 31, v168
	s_cmp_eq_u32 s4, 4
	v_lshlrev_b64 v[172:173], 11, v[168:169]
	v_mov_b32_e32 v126, v125
	v_mov_b32_e32 v118, v117
	v_pk_mul_f32 v[178:179], v[174:175], v[178:179] op_sel_hi:[0,1]
	v_mov_b32_e32 v116, v106
	v_mov_b32_e32 v117, v104
	v_mov_b32_e32 v124, v110
	v_mov_b32_e32 v125, v108
	v_pk_mul_f32 v[154:155], v[174:175], v[180:181] op_sel_hi:[0,1]
	v_mov_b32_e32 v104, v107
	v_mov_b32_e32 v108, v111
	s_cselect_b64 s[14:15], -1, 0
	s_cmp_lg_u32 s4, 4
	v_lshl_add_u64 v[172:173], v[166:167], 0, v[172:173]
	v_pk_fma_f32 v[176:177], v[176:177], v[126:127], v[118:119]
	v_pk_fma_f32 v[152:153], v[178:179], v[116:117], v[124:125]
	v_pk_fma_f32 v[106:107], v[154:155], v[104:105], v[108:109]
	v_cvt_pk_bf16_f32 v178, v158, v176
	v_cvt_pk_bf16_f32 v179, v159, v177
	s_nop 0
	v_cvt_pk_bf16_f32 v180, v153, v107
	v_cvt_pk_bf16_f32 v181, v152, v106
	global_store_dwordx4 v[172:173], v[178:181], off sc1
	s_cbranch_scc1 .LBB0_109
	v_pk_mul_f32 v[110:111], v[176:177], v[176:177]
	v_pk_mul_f32 v[106:107], v[106:107], v[106:107]
	v_pk_fma_f32 v[110:111], v[158:159], v[158:159], v[110:111]
	v_pk_fma_f32 v[106:107], v[152:153], v[152:153], v[106:107]
	v_add_f32_e32 v110, v110, v111
	v_add_f32_e32 v107, v107, v110
	v_add_f32_e32 v106, v106, v107
	v_max_f32_e32 v106, 0, v106
	s_branch .LBB0_110

.LBB0_110:
	v_cvt_f32_i32_e32 v111, v150
	v_cvt_f32_i32_e32 v110, v148
	v_cvt_f32_i32_e32 v151, v151
	v_cvt_f32_i32_e32 v150, v149
	v_mov_b32_e32 v175, v174
	v_pk_mul_f32 v[154:155], v[174:175], v[110:111]
	v_mov_b32_e32 v110, v88
	v_mov_b32_e32 v111, v90
	v_mov_b32_e32 v152, v68
	v_mov_b32_e32 v153, v70
	v_pk_fma_f32 v[176:177], v[154:155], v[110:111], v[152:153]
	v_pk_mul_f32 v[154:155], v[174:175], v[150:151]
	v_mov_b32_e32 v148, v89
	v_mov_b32_e32 v149, v91
	v_mov_b32_e32 v150, v69
	v_mov_b32_e32 v151, v71
	v_pk_fma_f32 v[178:179], v[154:155], v[148:149], v[150:151]
	v_cvt_f32_i32_e32 v155, v144
	v_cvt_f32_i32_e32 v154, v146
	v_cvt_f32_i32_e32 v145, v145
	v_cvt_f32_i32_e32 v144, v147
	v_mov_b32_e32 v158, v62
	v_pk_mul_f32 v[180:181], v[174:175], v[154:155]
	v_mov_b32_e32 v154, v94
	v_mov_b32_e32 v155, v92
	v_mov_b32_e32 v159, v60
	v_pk_mul_f32 v[174:175], v[174:175], v[144:145]
	v_mov_b32_e32 v144, v95
	v_mov_b32_e32 v145, v93
	v_mov_b32_e32 v146, v63
	v_mov_b32_e32 v147, v61
	v_cndmask_b32_e64 v169, 0, 1, s[14:15]
	v_mov_b32_e32 v107, v231
	v_pk_fma_f32 v[180:181], v[180:181], v[154:155], v[158:159]
	v_pk_fma_f32 v[174:175], v[174:175], v[144:145], v[146:147]
	v_cmp_ne_u32_e64 s[4:5], 1, v169
	s_andn2_b64 vcc, exec, s[14:15]
	v_cvt_pk_bf16_f32 v184, v176, v178
	v_cvt_pk_bf16_f32 v185, v177, v179
	v_cvt_pk_bf16_f32 v186, v181, v175
	v_cvt_pk_bf16_f32 v187, v180, v174
	global_store_dwordx4 v[172:173], v[184:187], off offset:256 sc1
	s_cbranch_vccnz .LBB0_112
	v_pk_mul_f32 v[172:173], v[178:179], v[178:179]
	v_pk_mul_f32 v[174:175], v[174:175], v[174:175]
	v_pk_fma_f32 v[172:173], v[176:177], v[176:177], v[172:173]
	v_pk_fma_f32 v[174:175], v[180:181], v[180:181], v[174:175]
	v_add_f32_e32 v169, v172, v173
	v_add_f32_e32 v169, v175, v169
	v_add_f32_e32 v169, v174, v169
	v_max_f32_e32 v107, v107, v107
	v_max_f32_e32 v107, v107, v169
.LBB0_112:
	ds_read_b32 v172, v165 offset:2112
	v_cvt_f32_i32_e32 v177, v142
	v_cvt_f32_i32_e32 v176, v140
	v_cvt_f32_i32_e32 v179, v143
	v_cvt_f32_i32_e32 v178, v141
	v_add_u32_e32 v174, 16, v168
	v_ashrrev_i32_e32 v175, 31, v174
	v_lshlrev_b64 v[174:175], 11, v[174:175]
	v_lshl_add_u64 v[140:141], v[166:167], 0, v[174:175]
	s_waitcnt lgkmcnt(0)
	v_pk_mul_f32 v[142:143], v[172:173], v[176:177] op_sel_hi:[0,1]
	v_pk_mul_f32 v[174:175], v[172:173], v[178:179] op_sel_hi:[0,1]
	v_cvt_f32_i32_e32 v177, v136
	v_cvt_f32_i32_e32 v176, v138
	v_cvt_f32_i32_e32 v179, v137
	v_cvt_f32_i32_e32 v178, v139
	v_pk_fma_f32 v[138:139], v[174:175], v[126:127], v[118:119]
	v_pk_mul_f32 v[136:137], v[172:173], v[176:177] op_sel_hi:[0,1]
	v_pk_fma_f32 v[142:143], v[142:143], v[170:171], v[156:157]
	v_pk_mul_f32 v[174:175], v[172:173], v[178:179] op_sel_hi:[0,1]
	v_pk_fma_f32 v[136:137], v[136:137], v[116:117], v[124:125]
	v_pk_fma_f32 v[174:175], v[174:175], v[104:105], v[108:109]
	s_and_b64 vcc, exec, s[4:5]
	v_cvt_pk_bf16_f32 v176, v142, v138
	v_cvt_pk_bf16_f32 v177, v143, v139
	v_cvt_pk_bf16_f32 v178, v137, v175
	v_cvt_pk_bf16_f32 v179, v136, v174
	global_store_dwordx4 v[140:141], v[176:179], off sc1
	s_cbranch_vccnz .LBB0_114
	v_pk_mul_f32 v[138:139], v[138:139], v[138:139]
	v_max_f32_e32 v106, v106, v106
	v_pk_fma_f32 v[138:139], v[142:143], v[142:143], v[138:139]
	v_pk_mul_f32 v[142:143], v[174:175], v[174:175]
	v_add_f32_e32 v138, v138, v139
	v_pk_fma_f32 v[136:137], v[136:137], v[136:137], v[142:143]
	s_nop 0
	v_add_f32_e32 v137, v137, v138
	v_add_f32_e32 v136, v136, v137
	v_max_f32_e32 v106, v106, v136
.LBB0_114:
	v_cvt_f32_i32_e32 v137, v134
	v_cvt_f32_i32_e32 v136, v132
	v_cvt_f32_i32_e32 v135, v135
	v_cvt_f32_i32_e32 v134, v133
	v_mov_b32_e32 v173, v172
	v_pk_mul_f32 v[132:133], v[172:173], v[136:137]
	v_cvt_f32_i32_e32 v137, v128
	v_cvt_f32_i32_e32 v136, v130
	v_cvt_f32_i32_e32 v139, v129
	v_cvt_f32_i32_e32 v138, v131
	v_pk_mul_f32 v[134:135], v[172:173], v[134:135]
	v_pk_mul_f32 v[128:129], v[172:173], v[136:137]
	v_pk_fma_f32 v[130:131], v[134:135], v[148:149], v[150:151]
	v_pk_mul_f32 v[134:135], v[172:173], v[138:139]
	v_pk_fma_f32 v[132:133], v[132:133], v[110:111], v[152:153]
	v_pk_fma_f32 v[128:129], v[128:129], v[154:155], v[158:159]
	v_pk_fma_f32 v[134:135], v[134:135], v[144:145], v[146:147]
	s_and_b64 vcc, exec, s[4:5]
	v_cvt_pk_bf16_f32 v136, v132, v130
	v_cvt_pk_bf16_f32 v137, v133, v131
	v_cvt_pk_bf16_f32 v138, v129, v135
	v_cvt_pk_bf16_f32 v139, v128, v134
	global_store_dwordx4 v[140:141], v[136:139], off offset:256 sc1
	s_cbranch_vccnz .LBB0_116
	v_pk_mul_f32 v[130:131], v[130:131], v[130:131]
	v_max_f32_e32 v107, v107, v107
	v_pk_fma_f32 v[130:131], v[132:133], v[132:133], v[130:131]
	v_pk_mul_f32 v[132:133], v[134:135], v[134:135]
	v_add_f32_e32 v130, v130, v131
	v_pk_fma_f32 v[128:129], v[128:129], v[128:129], v[132:133]
	s_nop 0
	v_add_f32_e32 v129, v129, v130
	v_add_f32_e32 v128, v128, v129
	v_max_f32_e32 v107, v107, v128
.LBB0_116:
	ds_read_b32 v128, v165 offset:2176
	v_cvt_f32_i32_e32 v133, v122
	v_cvt_f32_i32_e32 v132, v120
	v_cvt_f32_i32_e32 v135, v123
	v_cvt_f32_i32_e32 v134, v121
	v_add_u32_e32 v130, 32, v168
	v_ashrrev_i32_e32 v131, 31, v130
	v_lshlrev_b64 v[130:131], 11, v[130:131]
	v_lshl_add_u64 v[120:121], v[166:167], 0, v[130:131]
	s_waitcnt lgkmcnt(0)
	v_pk_mul_f32 v[122:123], v[128:129], v[132:133] op_sel_hi:[0,1]
	v_pk_mul_f32 v[130:131], v[128:129], v[134:135] op_sel_hi:[0,1]
	v_cvt_f32_i32_e32 v133, v112
	v_cvt_f32_i32_e32 v132, v114
	v_cvt_f32_i32_e32 v135, v113
	v_cvt_f32_i32_e32 v134, v115
	v_pk_fma_f32 v[114:115], v[130:131], v[126:127], v[118:119]
	v_pk_mul_f32 v[112:113], v[128:129], v[132:133] op_sel_hi:[0,1]
	v_pk_fma_f32 v[122:123], v[122:123], v[170:171], v[156:157]
	v_pk_mul_f32 v[130:131], v[128:129], v[134:135] op_sel_hi:[0,1]
	v_pk_fma_f32 v[112:113], v[112:113], v[116:117], v[124:125]
	v_pk_fma_f32 v[130:131], v[130:131], v[104:105], v[108:109]
	s_and_b64 vcc, exec, s[4:5]
	v_cvt_pk_bf16_f32 v132, v122, v114
	v_cvt_pk_bf16_f32 v133, v123, v115
	v_cvt_pk_bf16_f32 v134, v113, v131
	v_cvt_pk_bf16_f32 v135, v112, v130
	global_store_dwordx4 v[120:121], v[132:135], off sc1
	s_cbranch_vccnz .LBB0_118
	v_pk_mul_f32 v[114:115], v[114:115], v[114:115]
	v_max_f32_e32 v106, v106, v106
	v_pk_fma_f32 v[114:115], v[122:123], v[122:123], v[114:115]
	v_pk_mul_f32 v[122:123], v[130:131], v[130:131]
	v_add_f32_e32 v114, v114, v115
	v_pk_fma_f32 v[112:113], v[112:113], v[112:113], v[122:123]
	s_nop 0
	v_add_f32_e32 v113, v113, v114
	v_add_f32_e32 v112, v112, v113
	v_max_f32_e32 v106, v106, v112
.LBB0_118:
	v_cvt_f32_i32_e32 v113, v102
	v_cvt_f32_i32_e32 v112, v100
	v_cvt_f32_i32_e32 v103, v103
	v_cvt_f32_i32_e32 v102, v101
	v_mov_b32_e32 v129, v128
	v_pk_mul_f32 v[100:101], v[128:129], v[112:113]
	v_cvt_f32_i32_e32 v113, v96
	v_cvt_f32_i32_e32 v112, v98
	v_cvt_f32_i32_e32 v115, v97
	v_cvt_f32_i32_e32 v114, v99
	v_pk_mul_f32 v[102:103], v[128:129], v[102:103]
	v_pk_mul_f32 v[96:97], v[128:129], v[112:113]
	v_pk_fma_f32 v[98:99], v[102:103], v[148:149], v[150:151]
	v_pk_mul_f32 v[102:103], v[128:129], v[114:115]
	v_pk_fma_f32 v[100:101], v[100:101], v[110:111], v[152:153]
	v_pk_fma_f32 v[96:97], v[96:97], v[154:155], v[158:159]
	v_pk_fma_f32 v[102:103], v[102:103], v[144:145], v[146:147]
	s_and_b64 vcc, exec, s[4:5]
	v_cvt_pk_bf16_f32 v112, v100, v98
	v_cvt_pk_bf16_f32 v113, v101, v99
	v_cvt_pk_bf16_f32 v114, v97, v103
	v_cvt_pk_bf16_f32 v115, v96, v102
	global_store_dwordx4 v[120:121], v[112:115], off offset:256 sc1
	s_cbranch_vccnz .LBB0_120
	v_pk_mul_f32 v[98:99], v[98:99], v[98:99]
	s_nop 0
	v_pk_fma_f32 v[98:99], v[100:101], v[100:101], v[98:99]
	v_pk_mul_f32 v[100:101], v[102:103], v[102:103]
	v_add_f32_e32 v98, v98, v99
	v_pk_fma_f32 v[96:97], v[96:97], v[96:97], v[100:101]
	s_nop 0
	v_add_f32_e32 v97, v97, v98
	v_add_f32_e32 v96, v96, v97
	v_max_f32_e32 v97, v107, v107
	v_max_f32_e32 v107, v97, v96
.LBB0_120:
	ds_read_b32 v96, v165 offset:2240
	v_cvt_f32_i32_e32 v101, v86
	v_cvt_f32_i32_e32 v100, v84
	v_cvt_f32_i32_e32 v103, v87
	v_cvt_f32_i32_e32 v102, v85
	v_add_u32_e32 v98, 48, v168
	v_ashrrev_i32_e32 v99, 31, v98
	v_lshlrev_b64 v[98:99], 11, v[98:99]
	v_lshl_add_u64 v[84:85], v[166:167], 0, v[98:99]
	s_waitcnt lgkmcnt(0)
	v_pk_mul_f32 v[86:87], v[96:97], v[100:101] op_sel_hi:[0,1]
	v_pk_mul_f32 v[98:99], v[96:97], v[102:103] op_sel_hi:[0,1]
	v_cvt_f32_i32_e32 v101, v80
	v_cvt_f32_i32_e32 v100, v82
	v_cvt_f32_i32_e32 v103, v81
	v_cvt_f32_i32_e32 v102, v83
	v_pk_fma_f32 v[82:83], v[98:99], v[126:127], v[118:119]
	v_pk_mul_f32 v[80:81], v[96:97], v[100:101] op_sel_hi:[0,1]
	v_pk_fma_f32 v[86:87], v[86:87], v[170:171], v[156:157]
	v_pk_mul_f32 v[98:99], v[96:97], v[102:103] op_sel_hi:[0,1]
	v_pk_fma_f32 v[80:81], v[80:81], v[116:117], v[124:125]
	v_pk_fma_f32 v[98:99], v[98:99], v[104:105], v[108:109]
	s_and_b64 vcc, exec, s[4:5]
	v_cvt_pk_bf16_f32 v100, v86, v82
	v_cvt_pk_bf16_f32 v101, v87, v83
	v_cvt_pk_bf16_f32 v102, v81, v99
	v_cvt_pk_bf16_f32 v103, v80, v98
	global_store_dwordx4 v[84:85], v[100:103], off sc1
	s_cbranch_vccnz .LBB0_122
	v_pk_mul_f32 v[82:83], v[82:83], v[82:83]
	s_nop 0
	v_pk_fma_f32 v[82:83], v[86:87], v[86:87], v[82:83]
	v_pk_mul_f32 v[86:87], v[98:99], v[98:99]
	v_add_f32_e32 v82, v82, v83
	v_pk_fma_f32 v[80:81], v[80:81], v[80:81], v[86:87]
	s_nop 0
	v_add_f32_e32 v81, v81, v82
	v_add_f32_e32 v80, v80, v81
	v_max_f32_e32 v81, v106, v106
	v_max_f32_e32 v106, v81, v80
.LBB0_122:
	v_cvt_f32_i32_e32 v81, v78
	v_cvt_f32_i32_e32 v80, v76
	v_cvt_f32_i32_e32 v79, v79
	v_cvt_f32_i32_e32 v78, v77
	v_mov_b32_e32 v97, v96
	v_pk_mul_f32 v[76:77], v[96:97], v[80:81]
	v_cvt_f32_i32_e32 v81, v72
	v_cvt_f32_i32_e32 v80, v74
	v_cvt_f32_i32_e32 v83, v73
	v_cvt_f32_i32_e32 v82, v75
	v_pk_mul_f32 v[78:79], v[96:97], v[78:79]
	v_pk_mul_f32 v[72:73], v[96:97], v[80:81]
	v_pk_fma_f32 v[74:75], v[78:79], v[148:149], v[150:151]
	v_pk_mul_f32 v[78:79], v[96:97], v[82:83]
	v_pk_fma_f32 v[76:77], v[76:77], v[110:111], v[152:153]
	v_pk_fma_f32 v[72:73], v[72:73], v[154:155], v[158:159]
	v_pk_fma_f32 v[78:79], v[78:79], v[144:145], v[146:147]
	s_and_b64 vcc, exec, s[4:5]
	v_cvt_pk_bf16_f32 v80, v76, v74
	v_cvt_pk_bf16_f32 v81, v77, v75
	v_cvt_pk_bf16_f32 v82, v73, v79
	v_cvt_pk_bf16_f32 v83, v72, v78
	global_store_dwordx4 v[84:85], v[80:83], off offset:256 sc1
	s_cbranch_vccnz .LBB0_124
	v_pk_mul_f32 v[74:75], v[74:75], v[74:75]
	s_nop 0
	v_pk_fma_f32 v[74:75], v[76:77], v[76:77], v[74:75]
	v_pk_mul_f32 v[76:77], v[78:79], v[78:79]
	v_add_f32_e32 v74, v74, v75
	v_pk_fma_f32 v[72:73], v[72:73], v[72:73], v[76:77]
	s_nop 0
	v_add_f32_e32 v73, v73, v74
	v_add_f32_e32 v72, v72, v73
	v_max_f32_e32 v73, v107, v107
	v_max_f32_e32 v107, v73, v72
.LBB0_124:
	ds_read_b32 v72, v165 offset:2560
	v_cvt_f32_i32_e32 v77, v66
	v_cvt_f32_i32_e32 v76, v64
	v_cvt_f32_i32_e32 v79, v67
	v_cvt_f32_i32_e32 v78, v65
	v_add_u32_e32 v74, 0x80, v168
	v_ashrrev_i32_e32 v75, 31, v74
	v_lshlrev_b64 v[74:75], 11, v[74:75]
	v_lshl_add_u64 v[64:65], v[166:167], 0, v[74:75]
	s_waitcnt lgkmcnt(0)
	v_pk_mul_f32 v[66:67], v[72:73], v[76:77] op_sel_hi:[0,1]
	v_pk_mul_f32 v[74:75], v[72:73], v[78:79] op_sel_hi:[0,1]
	v_cvt_f32_i32_e32 v77, v56
	v_cvt_f32_i32_e32 v76, v58
	v_cvt_f32_i32_e32 v79, v57
	v_cvt_f32_i32_e32 v78, v59
	v_pk_fma_f32 v[58:59], v[74:75], v[126:127], v[118:119]
	v_pk_mul_f32 v[56:57], v[72:73], v[76:77] op_sel_hi:[0,1]
	v_pk_fma_f32 v[66:67], v[66:67], v[170:171], v[156:157]
	v_pk_mul_f32 v[74:75], v[72:73], v[78:79] op_sel_hi:[0,1]
	v_pk_fma_f32 v[56:57], v[56:57], v[116:117], v[124:125]
	v_pk_fma_f32 v[74:75], v[74:75], v[104:105], v[108:109]
	s_and_b64 vcc, exec, s[4:5]
	v_cvt_pk_bf16_f32 v76, v66, v58
	v_cvt_pk_bf16_f32 v77, v67, v59
	v_cvt_pk_bf16_f32 v78, v57, v75
	v_cvt_pk_bf16_f32 v79, v56, v74
	global_store_dwordx4 v[64:65], v[76:79], off sc1
	s_cbranch_vccnz .LBB0_126
	v_pk_mul_f32 v[58:59], v[58:59], v[58:59]
	s_nop 0
	v_pk_fma_f32 v[58:59], v[66:67], v[66:67], v[58:59]
	v_pk_mul_f32 v[66:67], v[74:75], v[74:75]
	v_add_f32_e32 v58, v58, v59
	v_pk_fma_f32 v[56:57], v[56:57], v[56:57], v[66:67]
	s_nop 0
	v_add_f32_e32 v57, v57, v58
	v_add_f32_e32 v56, v56, v57
	v_max_f32_e32 v57, v106, v106
	v_max_f32_e32 v106, v57, v56
.LBB0_126:
	v_cvt_f32_i32_e32 v57, v54
	v_cvt_f32_i32_e32 v56, v52
	v_cvt_f32_i32_e32 v55, v55
	v_cvt_f32_i32_e32 v54, v53
	v_mov_b32_e32 v73, v72
	v_pk_mul_f32 v[52:53], v[72:73], v[56:57]
	v_cvt_f32_i32_e32 v57, v48
	v_cvt_f32_i32_e32 v56, v50
	v_cvt_f32_i32_e32 v59, v49
	v_cvt_f32_i32_e32 v58, v51
	v_pk_mul_f32 v[54:55], v[72:73], v[54:55]
	v_pk_mul_f32 v[48:49], v[72:73], v[56:57]
	v_pk_fma_f32 v[50:51], v[54:55], v[148:149], v[150:151]
	v_pk_mul_f32 v[54:55], v[72:73], v[58:59]
	v_pk_fma_f32 v[52:53], v[52:53], v[110:111], v[152:153]
	v_pk_fma_f32 v[48:49], v[48:49], v[154:155], v[158:159]
	v_pk_fma_f32 v[54:55], v[54:55], v[144:145], v[146:147]
	s_and_b64 vcc, exec, s[4:5]
	v_cvt_pk_bf16_f32 v56, v52, v50
	v_cvt_pk_bf16_f32 v57, v53, v51
	v_cvt_pk_bf16_f32 v58, v49, v55
	v_cvt_pk_bf16_f32 v59, v48, v54
	global_store_dwordx4 v[64:65], v[56:59], off offset:256 sc1
	s_cbranch_vccnz .LBB0_128
	v_pk_mul_f32 v[50:51], v[50:51], v[50:51]
	s_nop 0
	v_pk_fma_f32 v[50:51], v[52:53], v[52:53], v[50:51]
	v_pk_mul_f32 v[52:53], v[54:55], v[54:55]
	v_add_f32_e32 v50, v50, v51
	v_pk_fma_f32 v[48:49], v[48:49], v[48:49], v[52:53]
	s_nop 0
	v_add_f32_e32 v49, v49, v50
	v_add_f32_e32 v48, v48, v49
	v_max_f32_e32 v49, v107, v107
	v_max_f32_e32 v107, v49, v48
.LBB0_128:
	ds_read_b32 v48, v165 offset:2624
	v_cvt_f32_i32_e32 v53, v46
	v_cvt_f32_i32_e32 v52, v44
	v_cvt_f32_i32_e32 v55, v47
	v_cvt_f32_i32_e32 v54, v45
	v_add_u32_e32 v50, 0x90, v168
	v_ashrrev_i32_e32 v51, 31, v50
	v_lshlrev_b64 v[50:51], 11, v[50:51]
	v_lshl_add_u64 v[44:45], v[166:167], 0, v[50:51]
	s_waitcnt lgkmcnt(0)
	v_pk_mul_f32 v[46:47], v[48:49], v[52:53] op_sel_hi:[0,1]
	v_pk_mul_f32 v[50:51], v[48:49], v[54:55] op_sel_hi:[0,1]
	v_cvt_f32_i32_e32 v53, v40
	v_cvt_f32_i32_e32 v52, v42
	v_cvt_f32_i32_e32 v55, v41
	v_cvt_f32_i32_e32 v54, v43
	v_pk_fma_f32 v[42:43], v[50:51], v[126:127], v[118:119]
	v_pk_mul_f32 v[40:41], v[48:49], v[52:53] op_sel_hi:[0,1]
	v_pk_fma_f32 v[46:47], v[46:47], v[170:171], v[156:157]
	v_pk_mul_f32 v[50:51], v[48:49], v[54:55] op_sel_hi:[0,1]
	v_pk_fma_f32 v[40:41], v[40:41], v[116:117], v[124:125]
	v_pk_fma_f32 v[50:51], v[50:51], v[104:105], v[108:109]
	s_and_b64 vcc, exec, s[4:5]
	v_cvt_pk_bf16_f32 v52, v46, v42
	v_cvt_pk_bf16_f32 v53, v47, v43
	v_cvt_pk_bf16_f32 v54, v41, v51
	v_cvt_pk_bf16_f32 v55, v40, v50
	global_store_dwordx4 v[44:45], v[52:55], off sc1
	s_cbranch_vccnz .LBB0_130
	v_pk_mul_f32 v[42:43], v[42:43], v[42:43]
	s_nop 0
	v_pk_fma_f32 v[42:43], v[46:47], v[46:47], v[42:43]
	v_pk_mul_f32 v[46:47], v[50:51], v[50:51]
	v_add_f32_e32 v42, v42, v43
	v_pk_fma_f32 v[40:41], v[40:41], v[40:41], v[46:47]
	s_nop 0
	v_add_f32_e32 v41, v41, v42
	v_add_f32_e32 v40, v40, v41
	v_max_f32_e32 v41, v106, v106
	v_max_f32_e32 v106, v41, v40
.LBB0_130:
	v_cvt_f32_i32_e32 v41, v38
	v_cvt_f32_i32_e32 v40, v36
	v_cvt_f32_i32_e32 v39, v39
	v_cvt_f32_i32_e32 v38, v37
	v_mov_b32_e32 v49, v48
	v_pk_mul_f32 v[36:37], v[48:49], v[40:41]
	v_cvt_f32_i32_e32 v41, v32
	v_cvt_f32_i32_e32 v40, v34
	v_cvt_f32_i32_e32 v43, v33
	v_cvt_f32_i32_e32 v42, v35
	v_pk_mul_f32 v[38:39], v[48:49], v[38:39]
	v_pk_mul_f32 v[32:33], v[48:49], v[40:41]
	v_pk_fma_f32 v[34:35], v[38:39], v[148:149], v[150:151]
	v_pk_mul_f32 v[38:39], v[48:49], v[42:43]
	v_pk_fma_f32 v[36:37], v[36:37], v[110:111], v[152:153]
	v_pk_fma_f32 v[32:33], v[32:33], v[154:155], v[158:159]
	v_pk_fma_f32 v[38:39], v[38:39], v[144:145], v[146:147]
	s_and_b64 vcc, exec, s[4:5]
	v_cvt_pk_bf16_f32 v40, v36, v34
	v_cvt_pk_bf16_f32 v41, v37, v35
	v_cvt_pk_bf16_f32 v42, v33, v39
	v_cvt_pk_bf16_f32 v43, v32, v38
	global_store_dwordx4 v[44:45], v[40:43], off offset:256 sc1
	s_cbranch_vccnz .LBB0_132
	v_pk_mul_f32 v[34:35], v[34:35], v[34:35]
	s_nop 0
	v_pk_fma_f32 v[34:35], v[36:37], v[36:37], v[34:35]
	v_pk_mul_f32 v[36:37], v[38:39], v[38:39]
	v_add_f32_e32 v34, v34, v35
	v_pk_fma_f32 v[32:33], v[32:33], v[32:33], v[36:37]
	s_nop 0
	v_add_f32_e32 v33, v33, v34
	v_add_f32_e32 v32, v32, v33
	v_max_f32_e32 v33, v107, v107
	v_max_f32_e32 v107, v33, v32
.LBB0_132:
	ds_read_b32 v32, v165 offset:2688
	v_cvt_f32_i32_e32 v37, v30
	v_cvt_f32_i32_e32 v36, v28
	v_cvt_f32_i32_e32 v39, v31
	v_cvt_f32_i32_e32 v38, v29
	v_add_u32_e32 v34, 0xa0, v168
	v_ashrrev_i32_e32 v35, 31, v34
	v_lshlrev_b64 v[34:35], 11, v[34:35]
	v_lshl_add_u64 v[28:29], v[166:167], 0, v[34:35]
	s_waitcnt lgkmcnt(0)
	v_pk_mul_f32 v[30:31], v[32:33], v[36:37] op_sel_hi:[0,1]
	v_pk_mul_f32 v[34:35], v[32:33], v[38:39] op_sel_hi:[0,1]
	v_cvt_f32_i32_e32 v37, v24
	v_cvt_f32_i32_e32 v36, v26
	v_cvt_f32_i32_e32 v39, v25
	v_cvt_f32_i32_e32 v38, v27
	v_pk_fma_f32 v[26:27], v[34:35], v[126:127], v[118:119]
	v_pk_mul_f32 v[24:25], v[32:33], v[36:37] op_sel_hi:[0,1]
	v_pk_fma_f32 v[30:31], v[30:31], v[170:171], v[156:157]
	v_pk_mul_f32 v[34:35], v[32:33], v[38:39] op_sel_hi:[0,1]
	v_pk_fma_f32 v[24:25], v[24:25], v[116:117], v[124:125]
	v_pk_fma_f32 v[34:35], v[34:35], v[104:105], v[108:109]
	s_and_b64 vcc, exec, s[4:5]
	v_cvt_pk_bf16_f32 v36, v30, v26
	v_cvt_pk_bf16_f32 v37, v31, v27
	v_cvt_pk_bf16_f32 v38, v25, v35
	v_cvt_pk_bf16_f32 v39, v24, v34
	global_store_dwordx4 v[28:29], v[36:39], off sc1
	s_cbranch_vccnz .LBB0_134
	v_pk_mul_f32 v[26:27], v[26:27], v[26:27]
	s_nop 0
	v_pk_fma_f32 v[26:27], v[30:31], v[30:31], v[26:27]
	v_pk_mul_f32 v[30:31], v[34:35], v[34:35]
	v_add_f32_e32 v26, v26, v27
	v_pk_fma_f32 v[24:25], v[24:25], v[24:25], v[30:31]
	s_nop 0
	v_add_f32_e32 v25, v25, v26
	v_add_f32_e32 v24, v24, v25
	v_max_f32_e32 v25, v106, v106
	v_max_f32_e32 v106, v25, v24
.LBB0_134:
	v_cvt_f32_i32_e32 v25, v22
	v_cvt_f32_i32_e32 v24, v20
	v_cvt_f32_i32_e32 v23, v23
	v_cvt_f32_i32_e32 v22, v21
	v_mov_b32_e32 v33, v32
	v_pk_mul_f32 v[20:21], v[32:33], v[24:25]
	v_cvt_f32_i32_e32 v25, v16
	v_cvt_f32_i32_e32 v24, v18
	v_cvt_f32_i32_e32 v27, v17
	v_cvt_f32_i32_e32 v26, v19
	v_pk_mul_f32 v[22:23], v[32:33], v[22:23]
	v_pk_mul_f32 v[16:17], v[32:33], v[24:25]
	v_pk_fma_f32 v[18:19], v[22:23], v[148:149], v[150:151]
	v_pk_mul_f32 v[22:23], v[32:33], v[26:27]
	v_pk_fma_f32 v[20:21], v[20:21], v[110:111], v[152:153]
	v_pk_fma_f32 v[16:17], v[16:17], v[154:155], v[158:159]
	v_pk_fma_f32 v[22:23], v[22:23], v[144:145], v[146:147]
	s_and_b64 vcc, exec, s[4:5]
	v_cvt_pk_bf16_f32 v24, v20, v18
	v_cvt_pk_bf16_f32 v25, v21, v19
	v_cvt_pk_bf16_f32 v26, v17, v23
	v_cvt_pk_bf16_f32 v27, v16, v22
	global_store_dwordx4 v[28:29], v[24:27], off offset:256 sc1
	s_cbranch_vccnz .LBB0_136
	v_pk_mul_f32 v[18:19], v[18:19], v[18:19]
	s_nop 0
	v_pk_fma_f32 v[18:19], v[20:21], v[20:21], v[18:19]
	v_pk_mul_f32 v[20:21], v[22:23], v[22:23]
	v_add_f32_e32 v18, v18, v19
	v_pk_fma_f32 v[16:17], v[16:17], v[16:17], v[20:21]
	s_nop 0
	v_add_f32_e32 v17, v17, v18
	v_add_f32_e32 v16, v16, v17
	v_max_f32_e32 v17, v107, v107
	v_max_f32_e32 v107, v17, v16
.LBB0_136:
	ds_read_b32 v18, v165 offset:2752
	v_cvt_f32_i32_e32 v21, v14
	v_cvt_f32_i32_e32 v15, v15
	v_cvt_f32_i32_e32 v14, v13
	v_cvt_f32_i32_e32 v20, v12
	v_cvt_f32_i32_e32 v9, v9
	v_add_u32_e32 v16, 0xb0, v168
	s_waitcnt lgkmcnt(0)
	v_pk_mul_f32 v[12:13], v[18:19], v[14:15] op_sel_hi:[0,1]
	v_cvt_f32_i32_e32 v15, v8
	v_cvt_f32_i32_e32 v14, v10
	v_cvt_f32_i32_e32 v8, v11
	v_ashrrev_i32_e32 v17, 31, v16
	v_lshlrev_b64 v[16:17], 11, v[16:17]
	v_pk_mul_f32 v[20:21], v[18:19], v[20:21] op_sel_hi:[0,1]
	v_pk_mul_f32 v[14:15], v[18:19], v[14:15] op_sel_hi:[0,1]
	v_pk_mul_f32 v[8:9], v[18:19], v[8:9] op_sel_hi:[0,1]
	v_lshl_add_u64 v[16:17], v[166:167], 0, v[16:17]
	v_pk_fma_f32 v[20:21], v[20:21], v[170:171], v[156:157]
	v_pk_fma_f32 v[12:13], v[12:13], v[126:127], v[118:119]
	v_pk_fma_f32 v[14:15], v[14:15], v[116:117], v[124:125]
	v_pk_fma_f32 v[8:9], v[8:9], v[104:105], v[108:109]
	s_and_b64 vcc, exec, s[4:5]
	v_cvt_pk_bf16_f32 v22, v20, v12
	v_cvt_pk_bf16_f32 v23, v21, v13
	v_cvt_pk_bf16_f32 v24, v15, v9
	v_cvt_pk_bf16_f32 v25, v14, v8
	global_store_dwordx4 v[16:17], v[22:25], off sc1
	s_cbranch_vccnz .LBB0_138
	v_pk_mul_f32 v[10:11], v[12:13], v[12:13]
	v_pk_mul_f32 v[8:9], v[8:9], v[8:9]
	v_pk_fma_f32 v[10:11], v[20:21], v[20:21], v[10:11]
	v_pk_fma_f32 v[8:9], v[14:15], v[14:15], v[8:9]
	v_add_f32_e32 v10, v10, v11
	v_add_f32_e32 v9, v9, v10
	v_add_f32_e32 v8, v8, v9
	v_max_f32_e32 v9, v106, v106
	v_max_f32_e32 v106, v9, v8
.LBB0_138:
	v_cvt_f32_i32_e32 v6, v6
	v_cvt_f32_i32_e32 v8, v2
	v_cvt_f32_i32_e32 v4, v4
	v_cvt_f32_i32_e32 v0, v0
	v_mul_f32_e32 v2, v18, v6
	v_cvt_f32_i32_e32 v6, v7
	v_cvt_f32_i32_e32 v5, v5
	v_cvt_f32_i32_e32 v1, v1
	v_mul_f32_e32 v7, v18, v8
	v_cvt_f32_i32_e32 v8, v3
	v_mul_f32_e32 v6, v18, v6
	v_mul_f32_e32 v4, v18, v4
	v_mul_f32_e32 v0, v18, v0
	v_mul_f32_e32 v5, v18, v5
	v_mul_f32_e32 v1, v18, v1
	v_fmac_f32_e32 v71, v6, v91
	v_mul_f32_e32 v6, v18, v8
	v_fma_f32 v4, v4, v88, v68
	v_fma_f32 v0, v0, v92, v60
	v_fma_f32 v5, v5, v89, v69
	v_fma_f32 v1, v1, v93, v61
	v_fma_f32 v2, v2, v90, v70
	v_fma_f32 v3, v7, v94, v62
	v_fmac_f32_e32 v63, v6, v95
	s_and_b64 vcc, exec, s[4:5]
	v_cvt_pk_bf16_f32 v6, v4, v5
	v_cvt_pk_bf16_f32 v7, v2, v71
	v_cvt_pk_bf16_f32 v8, v0, v1
	v_cvt_pk_bf16_f32 v9, v3, v63
	global_store_dwordx4 v[16:17], v[6:9], off offset:256 sc1
	s_cbranch_vccnz .LBB0_102
	s_nop 0
	v_or_b32_e32 v6, v161, v163
	v_cmp_eq_u32_e32 vcc, 0, v6
	v_mbcnt_lo_u32_b32 v6, -1, 0
	v_mbcnt_hi_u32_b32 v6, -1, v6
	v_mbcnt_lo_u32_b32 v7, -1, 0
	v_mbcnt_hi_u32_b32 v7, -1, v7
	s_or_b32 s3, s7, s28
	v_lshlrev_b32_e32 v6, 2, v6
	v_xor_b32_e32 v6, 64, v6
	ds_bpermute_b32 v6, v6, v106
	v_lshlrev_b32_e32 v7, 2, v7
	v_xor_b32_e32 v7, 0x80, v7
	s_waitcnt lgkmcnt(0)
	v_add_f32_e32 v6, v106, v6
	ds_bpermute_b32 v7, v7, v6
	s_waitcnt lgkmcnt(0)
	v_add_f32_e32 v6, v6, v7
	v_mbcnt_lo_u32_b32 v7, -1, 0
	v_mbcnt_hi_u32_b32 v7, -1, v7
	s_nop 0
	v_lshlrev_b32_e32 v7, 2, v7
	v_xor_b32_e32 v7, 4, v7
	ds_bpermute_b32 v7, v7, v6
	s_waitcnt lgkmcnt(0)
	v_max_f32_e32 v7, v7, v7
	v_max_f32_e32 v6, v6, v7
	v_mbcnt_lo_u32_b32 v7, -1, 0
	v_mbcnt_hi_u32_b32 v7, -1, v7
	s_nop 0
	v_lshlrev_b32_e32 v7, 2, v7
	v_xor_b32_e32 v7, 8, v7
	ds_bpermute_b32 v7, v7, v6
	s_waitcnt lgkmcnt(0)
	v_max_f32_e32 v7, v7, v7
	v_max_f32_e32 v6, v6, v7
	v_mbcnt_lo_u32_b32 v7, -1, 0
	v_mbcnt_hi_u32_b32 v7, -1, v7
	s_nop 0
	v_lshlrev_b32_e32 v7, 2, v7
	v_xor_b32_e32 v7, 16, v7
	ds_bpermute_b32 v7, v7, v6
	s_waitcnt lgkmcnt(0)
	v_max_f32_e32 v7, v7, v7
	v_max_f32_e32 v6, v6, v7
	v_mbcnt_lo_u32_b32 v7, -1, 0
	v_mbcnt_hi_u32_b32 v7, -1, v7
	s_nop 0
	v_lshlrev_b32_e32 v7, 2, v7
	v_xor_b32_e32 v7, 32, v7
	ds_bpermute_b32 v7, v7, v6
	s_and_saveexec_b64 s[14:15], vcc
	s_cbranch_execz .LBB0_144
	s_waitcnt lgkmcnt(0)
	v_max_f32_e32 v7, v7, v7
	v_max_f32_e32 v6, v6, v6
	s_mov_b64 s[4:5], exec
	v_max_f32_e32 v6, v6, v7
	s_mov_b32 s7, 0

.LBB0_161:
	s_add_u32 s3, s4, 0xfffc0080
	s_addc_u32 s14, s5, -1
	s_cmp_eq_u32 s39, 12
	s_cselect_b32 s17, s7, s14
	s_cselect_b32 s16, s35, s3
	v_add_u32_e32 v129, s93, v143
	s_cselect_b32 s15, s9, s38
	s_cselect_b32 s14, s36, s37
	s_add_i32 s3, 0, 0x14000
	ds_read_b128 v[136:139], v129
	ds_read_b128 v[146:149], v129 offset:1024
	ds_read_b128 v[150:153], v129 offset:2048
	ds_read_b128 v[154:157], v129 offset:3072
	v_add_u32_e32 v129, s3, v143
	ds_read_b128 v[158:161], v129
	ds_read_b128 v[162:165], v129 offset:1024
	ds_read_b128 v[166:169], v129 offset:2048
	ds_read_b128 v[170:173], v129 offset:3072
	s_add_i32 m0, s22, 0xc000
	ds_read_b128 v[174:177], v144
	ds_read_b128 v[178:181], v144 offset:1024
	ds_read_b128 v[182:185], v144 offset:2048
	ds_read_b128 v[186:189], v144 offset:3072
	ds_read_b128 v[190:193], v144 offset:4096
	ds_read_b128 v[194:197], v144 offset:5120
	ds_read_b128 v[198:201], v144 offset:6144
	ds_read_b128 v[202:205], v144 offset:7168
	global_load_lds_dwordx4 v230, s[4:5]
	s_add_i32 m0, s22, 0xe000
	v_mov_b32_e32 v131, v231
	global_load_lds_dwordx4 v130, s[4:5]
	s_waitcnt vmcnt(8)
	s_waitcnt lgkmcnt(0)
	s_barrier
	s_setprio 1
	s_waitcnt lgkmcnt(0)
	v_mfma_f32_16x16x32_f16 v[124:127], v[136:139], v[174:177], v[124:127]
	v_mfma_f32_16x16x32_f16 v[120:123], v[150:153], v[174:177], v[120:123]
	v_mfma_f32_16x16x32_f16 v[108:111], v[136:139], v[182:185], v[108:111]
	v_mfma_f32_16x16x32_f16 v[104:107], v[150:153], v[182:185], v[104:107]
	v_mfma_f32_16x16x32_f16 v[92:95], v[136:139], v[190:193], v[92:95]
	v_mfma_f32_16x16x32_f16 v[88:91], v[150:153], v[190:193], v[88:91]
	v_mfma_f32_16x16x32_f16 v[76:79], v[136:139], v[198:201], v[76:79]
	v_mfma_f32_16x16x32_f16 v[72:75], v[150:153], v[198:201], v[72:75]
	v_mfma_f32_16x16x32_f16 v[124:127], v[146:149], v[178:181], v[124:127]
	v_mfma_f32_16x16x32_f16 v[120:123], v[154:157], v[178:181], v[120:123]
	v_mfma_f32_16x16x32_f16 v[108:111], v[146:149], v[186:189], v[108:111]
	v_mfma_f32_16x16x32_f16 v[104:107], v[154:157], v[186:189], v[104:107]
	v_mfma_f32_16x16x32_f16 v[92:95], v[146:149], v[194:197], v[92:95]
	v_mfma_f32_16x16x32_f16 v[88:91], v[154:157], v[194:197], v[88:91]
	v_mfma_f32_16x16x32_f16 v[76:79], v[146:149], v[202:205], v[76:79]
	v_mfma_f32_16x16x32_f16 v[72:75], v[154:157], v[202:205], v[72:75]
	s_setprio 0
	s_setprio 1
	v_mfma_f32_16x16x32_f16 v[116:119], v[158:161], v[174:177], v[116:119]
	v_mfma_f32_16x16x32_f16 v[112:115], v[166:169], v[174:177], v[112:115]
	v_mfma_f32_16x16x32_f16 v[100:103], v[158:161], v[182:185], v[100:103]
	v_mfma_f32_16x16x32_f16 v[96:99], v[166:169], v[182:185], v[96:99]
	v_mfma_f32_16x16x32_f16 v[84:87], v[158:161], v[190:193], v[84:87]
	v_mfma_f32_16x16x32_f16 v[80:83], v[166:169], v[190:193], v[80:83]
	v_mfma_f32_16x16x32_f16 v[68:71], v[158:161], v[198:201], v[68:71]
	v_mfma_f32_16x16x32_f16 v[64:67], v[166:169], v[198:201], v[64:67]
	v_mfma_f32_16x16x32_f16 v[116:119], v[162:165], v[178:181], v[116:119]
	v_mfma_f32_16x16x32_f16 v[112:115], v[170:173], v[178:181], v[112:115]
	v_mfma_f32_16x16x32_f16 v[100:103], v[162:165], v[186:189], v[100:103]
	v_mfma_f32_16x16x32_f16 v[96:99], v[170:173], v[186:189], v[96:99]
	v_mfma_f32_16x16x32_f16 v[84:87], v[162:165], v[194:197], v[84:87]
	v_mfma_f32_16x16x32_f16 v[80:83], v[170:173], v[194:197], v[80:83]
	v_mfma_f32_16x16x32_f16 v[68:71], v[162:165], v[202:205], v[68:71]
	v_mfma_f32_16x16x32_f16 v[64:67], v[170:173], v[202:205], v[64:67]
	s_setprio 0
	s_barrier
	s_add_i32 s40, s93, s21
	s_mov_b32 m0, s40
	ds_read_b128 v[174:177], v144 offset:16384
	ds_read_b128 v[178:181], v144 offset:17408
	ds_read_b128 v[182:185], v144 offset:18432
	ds_read_b128 v[186:189], v144 offset:19456
	ds_read_b128 v[190:193], v144 offset:20480
	ds_read_b128 v[194:197], v144 offset:21504
	ds_read_b128 v[198:201], v144 offset:22528
	ds_read_b128 v[202:205], v144 offset:23552
	global_load_lds_dwordx4 v128, s[14:15]
	s_add_i32 m0, s40, 0x2000
	s_add_u32 s40, s14, 0x40000
	s_addc_u32 s41, s15, 0
	s_add_i32 s3, s3, s21
	global_load_lds_dwordx4 v132, s[14:15]
	s_mov_b32 m0, s3
	v_mov_b32_e32 v129, v231
	global_load_lds_dwordx4 v128, s[40:41]
	s_add_i32 m0, s3, 0x2000
	v_mov_b32_e32 v133, v231
	global_load_lds_dwordx4 v132, s[40:41]
	s_mov_b32 m0, s22
	v_lshl_add_u64 v[140:141], s[14:15], 0, v[128:129]
	global_load_lds_dwordx4 v230, s[16:17]
	s_mov_b32 m0, s23
	v_lshl_add_u64 v[206:207], s[14:15], 0, v[132:133]
	global_load_lds_dwordx4 v130, s[16:17]
	s_waitcnt vmcnt(8)
	s_waitcnt lgkmcnt(0)
	v_lshl_add_u64 v[208:209], s[16:17], 0, v[230:231]
	v_lshl_add_u64 v[210:211], s[16:17], 0, v[130:131]
	s_barrier
	s_setprio 1
	s_waitcnt lgkmcnt(0)
	v_mfma_f32_16x16x32_f16 v[60:63], v[136:139], v[174:177], v[60:63]
	v_mfma_f32_16x16x32_f16 v[56:59], v[150:153], v[174:177], v[56:59]
	v_mfma_f32_16x16x32_f16 v[44:47], v[136:139], v[182:185], v[44:47]
	v_mfma_f32_16x16x32_f16 v[40:43], v[150:153], v[182:185], v[40:43]
	v_mfma_f32_16x16x32_f16 v[28:31], v[136:139], v[190:193], v[28:31]
	v_mfma_f32_16x16x32_f16 v[24:27], v[150:153], v[190:193], v[24:27]
	v_mfma_f32_16x16x32_f16 v[12:15], v[136:139], v[198:201], v[12:15]
	v_mfma_f32_16x16x32_f16 v[8:11], v[150:153], v[198:201], v[8:11]
	v_mfma_f32_16x16x32_f16 v[60:63], v[146:149], v[178:181], v[60:63]
	v_mfma_f32_16x16x32_f16 v[56:59], v[154:157], v[178:181], v[56:59]
	v_mfma_f32_16x16x32_f16 v[44:47], v[146:149], v[186:189], v[44:47]
	v_mfma_f32_16x16x32_f16 v[40:43], v[154:157], v[186:189], v[40:43]
	v_mfma_f32_16x16x32_f16 v[28:31], v[146:149], v[194:197], v[28:31]
	v_mfma_f32_16x16x32_f16 v[24:27], v[154:157], v[194:197], v[24:27]
	v_mfma_f32_16x16x32_f16 v[12:15], v[146:149], v[202:205], v[12:15]
	v_mfma_f32_16x16x32_f16 v[8:11], v[154:157], v[202:205], v[8:11]
	s_setprio 0
	s_setprio 1
	v_mfma_f32_16x16x32_f16 v[52:55], v[158:161], v[174:177], v[52:55]
	v_mfma_f32_16x16x32_f16 v[48:51], v[166:169], v[174:177], v[48:51]
	v_mfma_f32_16x16x32_f16 v[36:39], v[158:161], v[182:185], v[36:39]
	v_mfma_f32_16x16x32_f16 v[32:35], v[166:169], v[182:185], v[32:35]
	v_mfma_f32_16x16x32_f16 v[20:23], v[158:161], v[190:193], v[20:23]
	v_mfma_f32_16x16x32_f16 v[16:19], v[166:169], v[190:193], v[16:19]
	v_mfma_f32_16x16x32_f16 v[4:7], v[158:161], v[198:201], v[4:7]
	v_mfma_f32_16x16x32_f16 v[0:3], v[166:169], v[198:201], v[0:3]
	v_mfma_f32_16x16x32_f16 v[52:55], v[162:165], v[178:181], v[52:55]
	v_mfma_f32_16x16x32_f16 v[48:51], v[170:173], v[178:181], v[48:51]
	v_mfma_f32_16x16x32_f16 v[36:39], v[162:165], v[186:189], v[36:39]
	v_mfma_f32_16x16x32_f16 v[32:35], v[170:173], v[186:189], v[32:35]
	v_mfma_f32_16x16x32_f16 v[20:23], v[162:165], v[194:197], v[20:23]
	v_mfma_f32_16x16x32_f16 v[16:19], v[170:173], v[194:197], v[16:19]
	v_mfma_f32_16x16x32_f16 v[4:7], v[162:165], v[202:205], v[4:7]
	v_mfma_f32_16x16x32_f16 v[0:3], v[170:173], v[202:205], v[0:3]
	s_setprio 0
	s_barrier
	v_add_u32_e32 v129, s2, v143
	s_add_i32 s3, 0, 0x1c000
	ds_read_b128 v[136:139], v129
	ds_read_b128 v[146:149], v129 offset:1024
	ds_read_b128 v[150:153], v129 offset:2048
	ds_read_b128 v[154:157], v129 offset:3072
	v_add_u32_e32 v129, s3, v143
	ds_read_b128 v[158:161], v129
	ds_read_b128 v[162:165], v129 offset:1024
	ds_read_b128 v[166:169], v129 offset:2048
	ds_read_b128 v[170:173], v129 offset:3072
	s_add_u32 s16, s16, 0x40000
	s_addc_u32 s17, s17, 0
	s_mov_b32 m0, s24
	ds_read_b128 v[174:177], v144 offset:32768
	ds_read_b128 v[178:181], v144 offset:33792
	ds_read_b128 v[182:185], v144 offset:34816
	ds_read_b128 v[186:189], v144 offset:35840
	ds_read_b128 v[190:193], v144 offset:36864
	ds_read_b128 v[194:197], v144 offset:37888
	ds_read_b128 v[198:201], v144 offset:38912
	ds_read_b128 v[202:205], v144 offset:39936
	global_load_lds_dwordx4 v230, s[16:17]
	s_mov_b32 m0, s25
	s_nop 0
	global_load_lds_dwordx4 v130, s[16:17]
	s_waitcnt vmcnt(8)
	s_waitcnt lgkmcnt(0)
	s_barrier
	s_setprio 1
	s_waitcnt lgkmcnt(0)
	v_mfma_f32_16x16x32_f16 v[124:127], v[136:139], v[174:177], v[124:127]
	v_mfma_f32_16x16x32_f16 v[120:123], v[150:153], v[174:177], v[120:123]
	v_mfma_f32_16x16x32_f16 v[108:111], v[136:139], v[182:185], v[108:111]
	v_mfma_f32_16x16x32_f16 v[104:107], v[150:153], v[182:185], v[104:107]
	v_mfma_f32_16x16x32_f16 v[92:95], v[136:139], v[190:193], v[92:95]
	v_mfma_f32_16x16x32_f16 v[88:91], v[150:153], v[190:193], v[88:91]
	v_mfma_f32_16x16x32_f16 v[76:79], v[136:139], v[198:201], v[76:79]
	v_mfma_f32_16x16x32_f16 v[72:75], v[150:153], v[198:201], v[72:75]
	v_mfma_f32_16x16x32_f16 v[124:127], v[146:149], v[178:181], v[124:127]
	v_mfma_f32_16x16x32_f16 v[120:123], v[154:157], v[178:181], v[120:123]
	v_mfma_f32_16x16x32_f16 v[108:111], v[146:149], v[186:189], v[108:111]
	v_mfma_f32_16x16x32_f16 v[104:107], v[154:157], v[186:189], v[104:107]
	v_mfma_f32_16x16x32_f16 v[92:95], v[146:149], v[194:197], v[92:95]
	v_mfma_f32_16x16x32_f16 v[88:91], v[154:157], v[194:197], v[88:91]
	v_mfma_f32_16x16x32_f16 v[76:79], v[146:149], v[202:205], v[76:79]
	v_mfma_f32_16x16x32_f16 v[72:75], v[154:157], v[202:205], v[72:75]
	s_setprio 0
	s_setprio 1
	v_mfma_f32_16x16x32_f16 v[116:119], v[158:161], v[174:177], v[116:119]
	v_mfma_f32_16x16x32_f16 v[112:115], v[166:169], v[174:177], v[112:115]
	v_mfma_f32_16x16x32_f16 v[100:103], v[158:161], v[182:185], v[100:103]
	v_mfma_f32_16x16x32_f16 v[96:99], v[166:169], v[182:185], v[96:99]
	v_mfma_f32_16x16x32_f16 v[84:87], v[158:161], v[190:193], v[84:87]
	v_mfma_f32_16x16x32_f16 v[80:83], v[166:169], v[190:193], v[80:83]
	v_mfma_f32_16x16x32_f16 v[68:71], v[158:161], v[198:201], v[68:71]
	v_mfma_f32_16x16x32_f16 v[64:67], v[166:169], v[198:201], v[64:67]
	v_mfma_f32_16x16x32_f16 v[116:119], v[162:165], v[178:181], v[116:119]
	v_mfma_f32_16x16x32_f16 v[112:115], v[170:173], v[178:181], v[112:115]
	v_mfma_f32_16x16x32_f16 v[100:103], v[162:165], v[186:189], v[100:103]
	v_mfma_f32_16x16x32_f16 v[96:99], v[170:173], v[186:189], v[96:99]
	v_mfma_f32_16x16x32_f16 v[84:87], v[162:165], v[194:197], v[84:87]
	v_mfma_f32_16x16x32_f16 v[80:83], v[170:173], v[194:197], v[80:83]
	v_mfma_f32_16x16x32_f16 v[68:71], v[162:165], v[202:205], v[68:71]
	v_mfma_f32_16x16x32_f16 v[64:67], v[170:173], v[202:205], v[64:67]
	s_setprio 0
	s_barrier
	s_add_i32 s16, s2, s21
	v_lshl_add_u64 v[140:141], v[140:141], 0, s[96:97]
	s_mov_b32 m0, s16
	ds_read_b128 v[174:177], v144 offset:49152
	ds_read_b128 v[178:181], v144 offset:50176
	ds_read_b128 v[182:185], v144 offset:51200
	ds_read_b128 v[186:189], v144 offset:52224
	ds_read_b128 v[190:193], v144 offset:53248
	ds_read_b128 v[194:197], v144 offset:54272
	ds_read_b128 v[198:201], v144 offset:55296
	ds_read_b128 v[202:205], v144 offset:56320
	global_load_lds_dwordx4 v[140:141], off
	s_add_i32 m0, s16, 0x2000
	s_add_u32 s14, s14, 0x40080
	v_lshl_add_u64 v[140:141], v[206:207], 0, s[96:97]
	s_addc_u32 s15, s15, 0
	s_add_i32 s3, s3, s21
	global_load_lds_dwordx4 v[140:141], off
	s_mov_b32 m0, s3
	v_lshl_add_u64 v[140:141], v[208:209], 0, s[96:97]
	global_load_lds_dwordx4 v128, s[14:15]
	s_add_i32 m0, s3, 0x2000
	s_nop 0
	global_load_lds_dwordx4 v132, s[14:15]
	s_mov_b32 m0, s29
	s_nop 0
	global_load_lds_dwordx4 v[140:141], off
	v_lshl_add_u64 v[140:141], v[210:211], 0, s[96:97]
	s_mov_b32 m0, s30
	s_nop 0
	global_load_lds_dwordx4 v[140:141], off
	s_waitcnt vmcnt(8)
	s_waitcnt lgkmcnt(0)
	s_barrier
	s_setprio 1
	s_waitcnt lgkmcnt(0)
	v_mfma_f32_16x16x32_f16 v[60:63], v[136:139], v[174:177], v[60:63]
	v_mfma_f32_16x16x32_f16 v[56:59], v[150:153], v[174:177], v[56:59]
	v_mfma_f32_16x16x32_f16 v[44:47], v[136:139], v[182:185], v[44:47]
	v_mfma_f32_16x16x32_f16 v[40:43], v[150:153], v[182:185], v[40:43]
	v_mfma_f32_16x16x32_f16 v[28:31], v[136:139], v[190:193], v[28:31]
	v_mfma_f32_16x16x32_f16 v[24:27], v[150:153], v[190:193], v[24:27]
	v_mfma_f32_16x16x32_f16 v[12:15], v[136:139], v[198:201], v[12:15]
	v_mfma_f32_16x16x32_f16 v[8:11], v[150:153], v[198:201], v[8:11]
	v_mfma_f32_16x16x32_f16 v[60:63], v[146:149], v[178:181], v[60:63]
	v_mfma_f32_16x16x32_f16 v[56:59], v[154:157], v[178:181], v[56:59]
	v_mfma_f32_16x16x32_f16 v[44:47], v[146:149], v[186:189], v[44:47]
	v_mfma_f32_16x16x32_f16 v[40:43], v[154:157], v[186:189], v[40:43]
	v_mfma_f32_16x16x32_f16 v[28:31], v[146:149], v[194:197], v[28:31]
	v_mfma_f32_16x16x32_f16 v[24:27], v[154:157], v[194:197], v[24:27]
	v_mfma_f32_16x16x32_f16 v[12:15], v[146:149], v[202:205], v[12:15]
	v_mfma_f32_16x16x32_f16 v[8:11], v[154:157], v[202:205], v[8:11]
	s_setprio 0
	s_setprio 1
	v_mfma_f32_16x16x32_f16 v[52:55], v[158:161], v[174:177], v[52:55]
	v_mfma_f32_16x16x32_f16 v[48:51], v[166:169], v[174:177], v[48:51]
	v_mfma_f32_16x16x32_f16 v[36:39], v[158:161], v[182:185], v[36:39]
	v_mfma_f32_16x16x32_f16 v[32:35], v[166:169], v[182:185], v[32:35]
	v_mfma_f32_16x16x32_f16 v[20:23], v[158:161], v[190:193], v[20:23]
	v_mfma_f32_16x16x32_f16 v[16:19], v[166:169], v[190:193], v[16:19]
	v_mfma_f32_16x16x32_f16 v[4:7], v[158:161], v[198:201], v[4:7]
	v_mfma_f32_16x16x32_f16 v[0:3], v[166:169], v[198:201], v[0:3]
	v_mfma_f32_16x16x32_f16 v[52:55], v[162:165], v[178:181], v[52:55]
	v_mfma_f32_16x16x32_f16 v[48:51], v[170:173], v[178:181], v[48:51]
	v_mfma_f32_16x16x32_f16 v[36:39], v[162:165], v[186:189], v[36:39]
	v_mfma_f32_16x16x32_f16 v[32:35], v[170:173], v[186:189], v[32:35]
	v_mfma_f32_16x16x32_f16 v[20:23], v[162:165], v[194:197], v[20:23]
	v_mfma_f32_16x16x32_f16 v[16:19], v[170:173], v[194:197], v[16:19]
	v_mfma_f32_16x16x32_f16 v[4:7], v[162:165], v[202:205], v[4:7]
	v_mfma_f32_16x16x32_f16 v[0:3], v[170:173], v[202:205], v[0:3]
	s_setprio 0
	s_barrier
	s_add_i32 s39, s39, 2
	s_add_u32 s4, s4, 0x100
	s_addc_u32 s5, s5, 0
	s_add_u32 s37, s37, 0x100
	s_addc_u32 s38, s38, 0
	s_cmp_gt_u32 s39, 13
	s_cbranch_scc0 .LBB0_161
	s_ashr_i32 s4, s34, 31
	s_lshr_b32 s4, s4, 30
	s_add_i32 s4, s34, s4
	s_ashr_i32 s14, s4, 2
	s_ashr_i32 s15, s14, 31
	s_lshl_b32 s3, s34, 8
	s_lshl_b64 s[4:5], s[14:15], 25
	s_add_u32 s16, s64, s4
	s_addc_u32 s17, s65, s5
	s_lshl_b32 s4, s14, 10
	s_sub_i32 s3, s3, s4
	s_add_i32 s4, s34, 3
	s_cmp_lt_u32 s4, 7
	s_cselect_b64 s[4:5], -1, 0
	v_cndmask_b32_e64 v134, 1.0, v213, s[4:5]
	v_pk_add_f32 v[124:125], v[124:125], 0 op_sel_hi:[1,0]
	v_pk_add_f32 v[126:127], v[126:127], 0 op_sel_hi:[1,0]
	v_pk_add_f32 v[122:123], v[122:123], 0 op_sel_hi:[1,0]
	v_pk_add_f32 v[120:121], v[120:121], 0 op_sel_hi:[1,0]
	v_pk_mul_f32 v[124:125], v[134:135], v[124:125] op_sel_hi:[0,1]
	v_mbcnt_lo_u32_b32 v129, -1, 0
	v_mbcnt_hi_u32_b32 v129, -1, v129
	v_pk_mul_f32 v[126:127], v[134:135], v[126:127] op_sel_hi:[0,1]
	v_pk_mul_f32 v[146:147], v[134:135], v[122:123] op_sel_hi:[0,1]
	v_pk_mul_f32 v[122:123], v[134:135], v[120:121] op_sel_hi:[0,1]
	v_mul_f32_e32 v121, v125, v125
	v_cvt_pk_bf16_f32 v120, v124, v125
	v_fmac_f32_e32 v121, v124, v124
	v_mul_f32_e32 v124, v127, v127
	v_fmac_f32_e32 v124, v126, v126
	s_or_b32 s7, s3, s28
	v_add_f32_e32 v121, v121, v124
	v_mul_f32_e32 v124, v123, v123
	v_lshl_add_u32 v138, s33, 8, v135
	v_or_b32_e32 v136, s7, v142
	v_fmac_f32_e32 v124, v122, v122
	v_ashrrev_i32_e32 v137, 31, v136
	v_ashrrev_i32_e32 v139, 31, v138
	v_add_f32_e32 v121, v121, v124
	v_mul_f32_e32 v124, v147, v147
	v_lshl_add_u64 v[140:141], v[136:137], 1, s[16:17]
	v_lshlrev_b64 v[136:137], 11, v[138:139]
	v_fmac_f32_e32 v124, v146, v146
	v_pk_add_f32 v[116:117], v[116:117], 0 op_sel_hi:[1,0]
	v_lshl_add_u64 v[136:137], v[140:141], 0, v[136:137]
	v_add_f32_e32 v124, v124, v121
	v_cvt_pk_bf16_f32 v121, v126, v127
	v_cvt_pk_bf16_f32 v122, v122, v123
	v_cvt_pk_bf16_f32 v123, v146, v147
	v_pk_add_f32 v[118:119], v[118:119], 0 op_sel_hi:[1,0]
	v_pk_add_f32 v[114:115], v[114:115], 0 op_sel_hi:[1,0]
	v_pk_add_f32 v[112:113], v[112:113], 0 op_sel_hi:[1,0]
	v_pk_mul_f32 v[116:117], v[134:135], v[116:117] op_sel_hi:[0,1]
	global_store_dwordx4 v[136:137], v[120:123], off sc1
	v_pk_mul_f32 v[118:119], v[134:135], v[118:119] op_sel_hi:[0,1]
	v_lshlrev_b32_e32 v129, 2, v129
	v_pk_mul_f32 v[122:123], v[134:135], v[114:115] op_sel_hi:[0,1]
	v_pk_mul_f32 v[114:115], v[134:135], v[112:113] op_sel_hi:[0,1]
	v_mul_f32_e32 v113, v117, v117
	v_cvt_pk_bf16_f32 v112, v116, v117
	v_fmac_f32_e32 v113, v116, v116
	v_mul_f32_e32 v116, v119, v119
	v_fmac_f32_e32 v116, v118, v118
	v_add_f32_e32 v113, v113, v116
	v_mul_f32_e32 v116, v115, v115
	v_fmac_f32_e32 v116, v114, v114
	v_add_f32_e32 v113, v113, v116
	v_mul_f32_e32 v116, v123, v123
	v_fmac_f32_e32 v116, v122, v122
	v_xor_b32_e32 v131, 64, v129
	v_add_f32_e32 v116, v116, v113
	ds_bpermute_b32 v117, v131, v116
	v_pk_add_f32 v[108:109], v[108:109], 0 op_sel_hi:[1,0]
	v_pk_add_f32 v[110:111], v[110:111], 0 op_sel_hi:[1,0]
	v_pk_add_f32 v[106:107], v[106:107], 0 op_sel_hi:[1,0]
	v_pk_add_f32 v[104:105], v[104:105], 0 op_sel_hi:[1,0]
	v_pk_mul_f32 v[108:109], v[134:135], v[108:109] op_sel_hi:[0,1]
	v_cvt_pk_bf16_f32 v113, v118, v119
	v_cvt_pk_bf16_f32 v114, v114, v115
	v_cvt_pk_bf16_f32 v115, v122, v123
	global_store_dwordx4 v[136:137], v[112:115], off offset:256 sc1
	v_pk_mul_f32 v[110:111], v[134:135], v[110:111] op_sel_hi:[0,1]
	v_pk_add_f32 v[100:101], v[100:101], 0 op_sel_hi:[1,0]
	s_waitcnt lgkmcnt(0)
	v_add_f32_e32 v112, v116, v117
	v_pk_mul_f32 v[116:117], v[134:135], v[106:107] op_sel_hi:[0,1]
	v_pk_mul_f32 v[106:107], v[134:135], v[104:105] op_sel_hi:[0,1]
	v_mul_f32_e32 v105, v109, v109
	v_cvt_pk_bf16_f32 v104, v108, v109
	v_fmac_f32_e32 v105, v108, v108
	v_mul_f32_e32 v108, v111, v111
	v_fmac_f32_e32 v108, v110, v110
	v_add_f32_e32 v105, v105, v108
	v_mul_f32_e32 v108, v107, v107
	v_or_b32_e32 v114, 16, v138
	v_fmac_f32_e32 v108, v106, v106
	v_ashrrev_i32_e32 v115, 31, v114
	v_add_f32_e32 v105, v105, v108
	v_mul_f32_e32 v108, v117, v117
	v_lshlrev_b64 v[114:115], 11, v[114:115]
	v_fmac_f32_e32 v108, v116, v116
	v_lshl_add_u64 v[114:115], v[140:141], 0, v[114:115]
	v_add_f32_e32 v108, v108, v105
	v_cvt_pk_bf16_f32 v105, v110, v111
	v_cvt_pk_bf16_f32 v106, v106, v107
	v_cvt_pk_bf16_f32 v107, v116, v117
	v_pk_add_f32 v[102:103], v[102:103], 0 op_sel_hi:[1,0]
	v_pk_add_f32 v[98:99], v[98:99], 0 op_sel_hi:[1,0]
	v_pk_add_f32 v[96:97], v[96:97], 0 op_sel_hi:[1,0]
	v_pk_mul_f32 v[100:101], v[134:135], v[100:101] op_sel_hi:[0,1]
	global_store_dwordx4 v[114:115], v[104:107], off sc1
	v_pk_mul_f32 v[102:103], v[134:135], v[102:103] op_sel_hi:[0,1]
	v_pk_add_f32 v[92:93], v[92:93], 0 op_sel_hi:[1,0]
	v_pk_mul_f32 v[106:107], v[134:135], v[98:99] op_sel_hi:[0,1]
	v_pk_mul_f32 v[98:99], v[134:135], v[96:97] op_sel_hi:[0,1]
	v_mul_f32_e32 v97, v101, v101
	v_cvt_pk_bf16_f32 v96, v100, v101
	v_fmac_f32_e32 v97, v100, v100
	v_mul_f32_e32 v100, v103, v103
	v_fmac_f32_e32 v100, v102, v102
	v_add_f32_e32 v97, v97, v100
	v_mul_f32_e32 v100, v99, v99
	v_fmac_f32_e32 v100, v98, v98
	v_add_f32_e32 v97, v97, v100
	v_mul_f32_e32 v100, v107, v107
	v_fmac_f32_e32 v100, v106, v106
	v_add_f32_e32 v100, v100, v97
	ds_bpermute_b32 v101, v131, v100
	v_pk_add_f32 v[94:95], v[94:95], 0 op_sel_hi:[1,0]
	v_pk_add_f32 v[90:91], v[90:91], 0 op_sel_hi:[1,0]
	v_pk_add_f32 v[88:89], v[88:89], 0 op_sel_hi:[1,0]
	v_pk_mul_f32 v[92:93], v[134:135], v[92:93] op_sel_hi:[0,1]
	v_cvt_pk_bf16_f32 v97, v102, v103
	v_cvt_pk_bf16_f32 v98, v98, v99
	v_cvt_pk_bf16_f32 v99, v106, v107
	global_store_dwordx4 v[114:115], v[96:99], off offset:256 sc1
	v_pk_mul_f32 v[94:95], v[134:135], v[94:95] op_sel_hi:[0,1]
	v_pk_add_f32 v[84:85], v[84:85], 0 op_sel_hi:[1,0]
	s_waitcnt lgkmcnt(0)
	v_add_f32_e32 v96, v100, v101
	v_pk_mul_f32 v[100:101], v[134:135], v[90:91] op_sel_hi:[0,1]
	v_pk_mul_f32 v[90:91], v[134:135], v[88:89] op_sel_hi:[0,1]
	v_mul_f32_e32 v89, v93, v93
	v_cvt_pk_bf16_f32 v88, v92, v93
	v_fmac_f32_e32 v89, v92, v92
	v_mul_f32_e32 v92, v95, v95
	v_fmac_f32_e32 v92, v94, v94
	v_add_f32_e32 v89, v89, v92
	v_mul_f32_e32 v92, v91, v91
	v_or_b32_e32 v98, 32, v138
	v_fmac_f32_e32 v92, v90, v90
	v_ashrrev_i32_e32 v99, 31, v98
	v_add_f32_e32 v89, v89, v92
	v_mul_f32_e32 v92, v101, v101
	v_lshlrev_b64 v[98:99], 11, v[98:99]
	v_fmac_f32_e32 v92, v100, v100
	v_lshl_add_u64 v[98:99], v[140:141], 0, v[98:99]
	v_add_f32_e32 v92, v92, v89
	v_cvt_pk_bf16_f32 v89, v94, v95
	v_cvt_pk_bf16_f32 v90, v90, v91
	v_cvt_pk_bf16_f32 v91, v100, v101
	v_pk_add_f32 v[86:87], v[86:87], 0 op_sel_hi:[1,0]
	v_pk_add_f32 v[82:83], v[82:83], 0 op_sel_hi:[1,0]
	v_pk_add_f32 v[80:81], v[80:81], 0 op_sel_hi:[1,0]
	v_pk_mul_f32 v[84:85], v[134:135], v[84:85] op_sel_hi:[0,1]
	global_store_dwordx4 v[98:99], v[88:91], off sc1
	v_pk_mul_f32 v[86:87], v[134:135], v[86:87] op_sel_hi:[0,1]
	v_pk_add_f32 v[76:77], v[76:77], 0 op_sel_hi:[1,0]
	v_pk_mul_f32 v[90:91], v[134:135], v[82:83] op_sel_hi:[0,1]
	v_pk_mul_f32 v[82:83], v[134:135], v[80:81] op_sel_hi:[0,1]
	v_mul_f32_e32 v81, v85, v85
	v_cvt_pk_bf16_f32 v80, v84, v85
	v_fmac_f32_e32 v81, v84, v84
	v_mul_f32_e32 v84, v87, v87
	v_fmac_f32_e32 v84, v86, v86
	v_add_f32_e32 v81, v81, v84
	v_mul_f32_e32 v84, v83, v83
	v_fmac_f32_e32 v84, v82, v82
	v_add_f32_e32 v81, v81, v84
	v_mul_f32_e32 v84, v91, v91
	v_fmac_f32_e32 v84, v90, v90
	v_add_f32_e32 v84, v84, v81
	ds_bpermute_b32 v85, v131, v84
	v_pk_add_f32 v[78:79], v[78:79], 0 op_sel_hi:[1,0]
	v_pk_add_f32 v[74:75], v[74:75], 0 op_sel_hi:[1,0]
	v_pk_add_f32 v[72:73], v[72:73], 0 op_sel_hi:[1,0]
	v_pk_mul_f32 v[76:77], v[134:135], v[76:77] op_sel_hi:[0,1]
	v_cvt_pk_bf16_f32 v81, v86, v87
	v_cvt_pk_bf16_f32 v82, v82, v83
	v_cvt_pk_bf16_f32 v83, v90, v91
	global_store_dwordx4 v[98:99], v[80:83], off offset:256 sc1
	v_pk_mul_f32 v[78:79], v[134:135], v[78:79] op_sel_hi:[0,1]
	v_pk_add_f32 v[68:69], v[68:69], 0 op_sel_hi:[1,0]
	s_waitcnt lgkmcnt(0)
	v_add_f32_e32 v80, v84, v85
	v_pk_mul_f32 v[84:85], v[134:135], v[74:75] op_sel_hi:[0,1]
	v_pk_mul_f32 v[74:75], v[134:135], v[72:73] op_sel_hi:[0,1]
	v_mul_f32_e32 v73, v77, v77
	v_cvt_pk_bf16_f32 v72, v76, v77
	v_fmac_f32_e32 v73, v76, v76
	v_mul_f32_e32 v76, v79, v79
	v_fmac_f32_e32 v76, v78, v78
	v_add_f32_e32 v73, v73, v76
	v_mul_f32_e32 v76, v75, v75
	v_or_b32_e32 v82, 48, v138
	v_fmac_f32_e32 v76, v74, v74
	v_ashrrev_i32_e32 v83, 31, v82
	v_add_f32_e32 v73, v73, v76
	v_mul_f32_e32 v76, v85, v85
	v_lshlrev_b64 v[82:83], 11, v[82:83]
	v_fmac_f32_e32 v76, v84, v84
	v_lshl_add_u64 v[82:83], v[140:141], 0, v[82:83]
	v_add_f32_e32 v76, v76, v73
	v_cvt_pk_bf16_f32 v73, v78, v79
	v_cvt_pk_bf16_f32 v74, v74, v75
	v_cvt_pk_bf16_f32 v75, v84, v85
	v_pk_add_f32 v[70:71], v[70:71], 0 op_sel_hi:[1,0]
	v_pk_add_f32 v[66:67], v[66:67], 0 op_sel_hi:[1,0]
	v_pk_add_f32 v[64:65], v[64:65], 0 op_sel_hi:[1,0]
	v_pk_mul_f32 v[68:69], v[134:135], v[68:69] op_sel_hi:[0,1]
	global_store_dwordx4 v[82:83], v[72:75], off sc1
	v_pk_mul_f32 v[70:71], v[134:135], v[70:71] op_sel_hi:[0,1]
	v_pk_add_f32 v[60:61], v[60:61], 0 op_sel_hi:[1,0]
	v_pk_mul_f32 v[74:75], v[134:135], v[66:67] op_sel_hi:[0,1]
	v_pk_mul_f32 v[66:67], v[134:135], v[64:65] op_sel_hi:[0,1]
	v_mul_f32_e32 v65, v69, v69
	v_cvt_pk_bf16_f32 v64, v68, v69
	v_fmac_f32_e32 v65, v68, v68
	v_mul_f32_e32 v68, v71, v71
	v_fmac_f32_e32 v68, v70, v70
	v_add_f32_e32 v65, v65, v68
	v_mul_f32_e32 v68, v67, v67
	v_fmac_f32_e32 v68, v66, v66
	v_add_f32_e32 v65, v65, v68
	v_mul_f32_e32 v68, v75, v75
	v_fmac_f32_e32 v68, v74, v74
	v_add_f32_e32 v68, v68, v65
	ds_bpermute_b32 v69, v131, v68
	v_pk_add_f32 v[62:63], v[62:63], 0 op_sel_hi:[1,0]
	v_pk_add_f32 v[56:57], v[56:57], 0 op_sel_hi:[1,0]
	v_pk_mul_f32 v[60:61], v[134:135], v[60:61] op_sel_hi:[0,1]
	v_cvt_pk_bf16_f32 v65, v70, v71
	v_cvt_pk_bf16_f32 v66, v66, v67
	v_cvt_pk_bf16_f32 v67, v74, v75
	global_store_dwordx4 v[82:83], v[64:67], off offset:256 sc1
	v_pk_mul_f32 v[62:63], v[134:135], v[62:63] op_sel_hi:[0,1]
	v_pk_mul_f32 v[70:71], v[134:135], v[56:57] op_sel_hi:[0,1]
	v_cvt_pk_bf16_f32 v56, v60, v61
	v_mul_f32_e32 v61, v61, v61
	v_fmac_f32_e32 v61, v60, v60
	v_mul_f32_e32 v60, v63, v63
	v_fmac_f32_e32 v60, v62, v62
	v_pk_add_f32 v[58:59], v[58:59], 0 op_sel_hi:[1,0]
	v_add_f32_e32 v60, v61, v60
	v_mul_f32_e32 v61, v71, v71
	s_waitcnt lgkmcnt(0)
	v_add_f32_e32 v64, v68, v69
	v_pk_mul_f32 v[68:69], v[134:135], v[58:59] op_sel_hi:[0,1]
	v_fmac_f32_e32 v61, v70, v70
	v_add_f32_e32 v60, v60, v61
	v_mul_f32_e32 v61, v69, v69
	s_mov_b64 s[4:5], 0x40000
	v_fmac_f32_e32 v61, v68, v68
	s_mov_b32 s3, 0x40000
	v_lshl_add_u64 v[66:67], v[136:137], 0, s[4:5]
	v_cvt_pk_bf16_f32 v57, v62, v63
	v_add_f32_e32 v62, v61, v60
	v_add_co_u32_e64 v60, s[4:5], s3, v136
	v_pk_add_f32 v[52:53], v[52:53], 0 op_sel_hi:[1,0]
	v_cvt_pk_bf16_f32 v58, v70, v71
	v_cvt_pk_bf16_f32 v59, v68, v69
	s_nop 0
	v_addc_co_u32_e64 v61, s[4:5], 0, v137, s[4:5]
	v_pk_add_f32 v[54:55], v[54:55], 0 op_sel_hi:[1,0]
	v_pk_add_f32 v[50:51], v[50:51], 0 op_sel_hi:[1,0]
	v_pk_add_f32 v[48:49], v[48:49], 0 op_sel_hi:[1,0]
	v_pk_mul_f32 v[52:53], v[134:135], v[52:53] op_sel_hi:[0,1]
	global_store_dwordx4 v[60:61], v[56:59], off sc1
	v_pk_mul_f32 v[54:55], v[134:135], v[54:55] op_sel_hi:[0,1]
	v_pk_add_f32 v[44:45], v[44:45], 0 op_sel_hi:[1,0]
	v_pk_mul_f32 v[58:59], v[134:135], v[50:51] op_sel_hi:[0,1]
	v_pk_mul_f32 v[50:51], v[134:135], v[48:49] op_sel_hi:[0,1]
	v_mul_f32_e32 v49, v53, v53
	v_cvt_pk_bf16_f32 v48, v52, v53
	v_fmac_f32_e32 v49, v52, v52
	v_mul_f32_e32 v52, v55, v55
	v_fmac_f32_e32 v52, v54, v54
	v_add_f32_e32 v49, v49, v52
	v_mul_f32_e32 v52, v51, v51
	v_fmac_f32_e32 v52, v50, v50
	v_add_f32_e32 v49, v49, v52
	v_mul_f32_e32 v52, v59, v59
	v_fmac_f32_e32 v52, v58, v58
	v_add_f32_e32 v52, v52, v49
	ds_bpermute_b32 v53, v131, v52
	v_pk_add_f32 v[46:47], v[46:47], 0 op_sel_hi:[1,0]
	v_pk_add_f32 v[40:41], v[40:41], 0 op_sel_hi:[1,0]
	v_pk_mul_f32 v[44:45], v[134:135], v[44:45] op_sel_hi:[0,1]
	v_cvt_pk_bf16_f32 v49, v54, v55
	v_cvt_pk_bf16_f32 v50, v50, v51
	v_cvt_pk_bf16_f32 v51, v58, v59
	global_store_dwordx4 v[66:67], v[48:51], off offset:256 sc1
	v_pk_mul_f32 v[46:47], v[134:135], v[46:47] op_sel_hi:[0,1]
	v_pk_mul_f32 v[54:55], v[134:135], v[40:41] op_sel_hi:[0,1]
	v_cvt_pk_bf16_f32 v40, v44, v45
	v_mul_f32_e32 v45, v45, v45
	v_fmac_f32_e32 v45, v44, v44
	v_mul_f32_e32 v44, v47, v47
	v_fmac_f32_e32 v44, v46, v46
	v_pk_add_f32 v[42:43], v[42:43], 0 op_sel_hi:[1,0]
	v_add_f32_e32 v44, v45, v44
	v_mul_f32_e32 v45, v55, v55
	s_waitcnt lgkmcnt(0)
	v_add_f32_e32 v48, v52, v53
	v_pk_mul_f32 v[52:53], v[134:135], v[42:43] op_sel_hi:[0,1]
	v_fmac_f32_e32 v45, v54, v54
	v_add_f32_e32 v44, v44, v45
	v_mul_f32_e32 v45, v53, v53
	s_mov_b64 s[4:5], 0x48000
	v_fmac_f32_e32 v45, v52, v52
	s_mov_b32 s3, 0x48000
	v_lshl_add_u64 v[50:51], v[136:137], 0, s[4:5]
	v_cvt_pk_bf16_f32 v41, v46, v47
	v_add_f32_e32 v46, v45, v44
	v_add_co_u32_e64 v44, s[4:5], s3, v136
	v_pk_add_f32 v[36:37], v[36:37], 0 op_sel_hi:[1,0]
	v_cvt_pk_bf16_f32 v42, v54, v55
	v_cvt_pk_bf16_f32 v43, v52, v53
	s_nop 0
	v_addc_co_u32_e64 v45, s[4:5], 0, v137, s[4:5]
	v_pk_add_f32 v[38:39], v[38:39], 0 op_sel_hi:[1,0]
	v_pk_add_f32 v[34:35], v[34:35], 0 op_sel_hi:[1,0]
	v_pk_add_f32 v[32:33], v[32:33], 0 op_sel_hi:[1,0]
	v_pk_mul_f32 v[36:37], v[134:135], v[36:37] op_sel_hi:[0,1]
	global_store_dwordx4 v[44:45], v[40:43], off sc1
	v_pk_mul_f32 v[38:39], v[134:135], v[38:39] op_sel_hi:[0,1]
	v_pk_add_f32 v[28:29], v[28:29], 0 op_sel_hi:[1,0]
	v_pk_mul_f32 v[42:43], v[134:135], v[34:35] op_sel_hi:[0,1]
	v_pk_mul_f32 v[34:35], v[134:135], v[32:33] op_sel_hi:[0,1]
	v_mul_f32_e32 v33, v37, v37
	v_cvt_pk_bf16_f32 v32, v36, v37
	v_fmac_f32_e32 v33, v36, v36
	v_mul_f32_e32 v36, v39, v39
	v_fmac_f32_e32 v36, v38, v38
	v_add_f32_e32 v33, v33, v36
	v_mul_f32_e32 v36, v35, v35
	v_fmac_f32_e32 v36, v34, v34
	v_add_f32_e32 v33, v33, v36
	v_mul_f32_e32 v36, v43, v43
	v_fmac_f32_e32 v36, v42, v42
	v_add_f32_e32 v36, v36, v33
	ds_bpermute_b32 v37, v131, v36
	v_pk_add_f32 v[30:31], v[30:31], 0 op_sel_hi:[1,0]
	v_pk_add_f32 v[24:25], v[24:25], 0 op_sel_hi:[1,0]
	v_pk_mul_f32 v[28:29], v[134:135], v[28:29] op_sel_hi:[0,1]
	v_cvt_pk_bf16_f32 v33, v38, v39
	v_cvt_pk_bf16_f32 v34, v34, v35
	v_cvt_pk_bf16_f32 v35, v42, v43
	global_store_dwordx4 v[50:51], v[32:35], off offset:256 sc1
	v_pk_mul_f32 v[30:31], v[134:135], v[30:31] op_sel_hi:[0,1]
	v_pk_mul_f32 v[38:39], v[134:135], v[24:25] op_sel_hi:[0,1]
	v_cvt_pk_bf16_f32 v24, v28, v29
	v_mul_f32_e32 v29, v29, v29
	v_fmac_f32_e32 v29, v28, v28
	v_mul_f32_e32 v28, v31, v31
	v_fmac_f32_e32 v28, v30, v30
	v_pk_add_f32 v[26:27], v[26:27], 0 op_sel_hi:[1,0]
	v_add_f32_e32 v28, v29, v28
	v_mul_f32_e32 v29, v39, v39
	s_waitcnt lgkmcnt(0)
	v_add_f32_e32 v32, v36, v37
	v_pk_mul_f32 v[36:37], v[134:135], v[26:27] op_sel_hi:[0,1]
	v_fmac_f32_e32 v29, v38, v38
	v_add_f32_e32 v28, v28, v29
	v_mul_f32_e32 v29, v37, v37
	s_mov_b64 s[4:5], 0x50000
	v_fmac_f32_e32 v29, v36, v36
	s_mov_b32 s3, 0x50000
	v_lshl_add_u64 v[34:35], v[136:137], 0, s[4:5]
	v_cvt_pk_bf16_f32 v25, v30, v31
	v_add_f32_e32 v30, v29, v28
	v_add_co_u32_e64 v28, s[4:5], s3, v136
	v_pk_add_f32 v[20:21], v[20:21], 0 op_sel_hi:[1,0]
	v_cvt_pk_bf16_f32 v26, v38, v39
	v_cvt_pk_bf16_f32 v27, v36, v37
	s_nop 0
	v_addc_co_u32_e64 v29, s[4:5], 0, v137, s[4:5]
	v_pk_add_f32 v[22:23], v[22:23], 0 op_sel_hi:[1,0]
	v_pk_add_f32 v[18:19], v[18:19], 0 op_sel_hi:[1,0]
	v_pk_add_f32 v[16:17], v[16:17], 0 op_sel_hi:[1,0]
	v_pk_mul_f32 v[20:21], v[134:135], v[20:21] op_sel_hi:[0,1]
	global_store_dwordx4 v[28:29], v[24:27], off sc1
	v_pk_mul_f32 v[22:23], v[134:135], v[22:23] op_sel_hi:[0,1]
	s_mov_b64 s[4:5], 0x58000
	v_pk_mul_f32 v[26:27], v[134:135], v[18:19] op_sel_hi:[0,1]
	v_pk_mul_f32 v[18:19], v[134:135], v[16:17] op_sel_hi:[0,1]
	v_mul_f32_e32 v17, v21, v21
	v_cvt_pk_bf16_f32 v16, v20, v21
	v_fmac_f32_e32 v17, v20, v20
	v_mul_f32_e32 v20, v23, v23
	v_fmac_f32_e32 v20, v22, v22
	v_add_f32_e32 v17, v17, v20
	v_mul_f32_e32 v20, v19, v19
	v_fmac_f32_e32 v20, v18, v18
	v_add_f32_e32 v17, v17, v20
	v_mul_f32_e32 v20, v27, v27
	v_fmac_f32_e32 v20, v26, v26
	v_add_f32_e32 v20, v20, v17
	ds_bpermute_b32 v21, v131, v20
	v_cvt_pk_bf16_f32 v17, v22, v23
	v_cvt_pk_bf16_f32 v18, v18, v19
	v_cvt_pk_bf16_f32 v19, v26, v27
	s_mov_b32 s3, 0x58000
	global_store_dwordx4 v[34:35], v[16:19], off offset:256 sc1
	v_pk_add_f32 v[14:15], v[14:15], 0 op_sel_hi:[1,0]
	v_pk_add_f32 v[12:13], v[12:13], 0 op_sel_hi:[1,0]
	v_lshl_add_u64 v[18:19], v[136:137], 0, s[4:5]
	v_pk_add_f32 v[8:9], v[8:9], 0 op_sel_hi:[1,0]
	v_add_co_u32_e64 v26, s[4:5], s3, v136
	v_pk_add_f32 v[10:11], v[10:11], 0 op_sel_hi:[1,0]
	v_pk_mul_f32 v[14:15], v[134:135], v[14:15] op_sel_hi:[0,1]
	v_pk_mul_f32 v[12:13], v[134:135], v[12:13] op_sel_hi:[0,1]
	v_pk_mul_f32 v[22:23], v[134:135], v[8:9] op_sel_hi:[0,1]
	v_cvt_pk_bf16_f32 v8, v12, v13
	v_cvt_pk_bf16_f32 v9, v14, v15
	v_addc_co_u32_e64 v27, s[4:5], 0, v137, s[4:5]
	s_waitcnt lgkmcnt(0)
	v_add_f32_e32 v16, v20, v21
	v_pk_mul_f32 v[20:21], v[134:135], v[10:11] op_sel_hi:[0,1]
	v_cvt_pk_bf16_f32 v10, v22, v23
	v_cvt_pk_bf16_f32 v11, v20, v21
	global_store_dwordx4 v[26:27], v[8:11], off sc1
	v_pk_add_f32 v[6:7], v[6:7], 0 op_sel_hi:[1,0]
	v_pk_add_f32 v[4:5], v[4:5], 0 op_sel_hi:[1,0]
	v_mul_f32_e32 v8, v13, v13
	v_mul_f32_e32 v9, v15, v15
	v_fmac_f32_e32 v8, v12, v12
	v_fmac_f32_e32 v9, v14, v14
	v_add_f32_e32 v8, v8, v9
	v_mul_f32_e32 v9, v23, v23
	v_pk_add_f32 v[0:1], v[0:1], 0 op_sel_hi:[1,0]
	v_pk_mul_f32 v[6:7], v[134:135], v[6:7] op_sel_hi:[0,1]
	v_pk_mul_f32 v[4:5], v[134:135], v[4:5] op_sel_hi:[0,1]
	v_fmac_f32_e32 v9, v22, v22
	v_pk_mul_f32 v[10:11], v[134:135], v[0:1] op_sel_hi:[0,1]
	v_mul_f32_e32 v0, v5, v5
	v_mul_f32_e32 v1, v7, v7
	v_add_f32_e32 v8, v8, v9
	v_mul_f32_e32 v9, v21, v21
	v_fmac_f32_e32 v0, v4, v4
	v_fmac_f32_e32 v1, v6, v6
	v_fmac_f32_e32 v9, v20, v20
	v_pk_add_f32 v[2:3], v[2:3], 0 op_sel_hi:[1,0]
	v_add_f32_e32 v0, v0, v1
	v_mul_f32_e32 v1, v11, v11
	v_add_f32_e32 v12, v9, v8
	v_pk_mul_f32 v[8:9], v[134:135], v[2:3] op_sel_hi:[0,1]
	v_fmac_f32_e32 v1, v10, v10
	v_add_f32_e32 v0, v0, v1
	v_mul_f32_e32 v1, v9, v9
	v_fmac_f32_e32 v1, v8, v8
	v_add_f32_e32 v0, v1, v0
	ds_bpermute_b32 v125, v131, v124
	ds_bpermute_b32 v109, v131, v108
	ds_bpermute_b32 v93, v131, v92
	ds_bpermute_b32 v77, v131, v76
	ds_bpermute_b32 v63, v131, v62
	ds_bpermute_b32 v47, v131, v46
	ds_bpermute_b32 v31, v131, v30
	ds_bpermute_b32 v13, v131, v12
	ds_bpermute_b32 v1, v131, v0
	v_xor_b32_e32 v129, 0x80, v129
	s_waitcnt lgkmcnt(0)
	v_add_f32_e32 v120, v124, v125
	v_add_f32_e32 v104, v108, v109
	v_add_f32_e32 v88, v92, v93
	v_add_f32_e32 v72, v76, v77
	v_add_f32_e32 v56, v62, v63
	v_add_f32_e32 v40, v46, v47
	v_add_f32_e32 v24, v30, v31
	v_add_f32_e32 v2, v12, v13
	v_add_f32_e32 v0, v0, v1
	ds_bpermute_b32 v121, v129, v120
	ds_bpermute_b32 v113, v129, v112
	ds_bpermute_b32 v105, v129, v104
	ds_bpermute_b32 v97, v129, v96
	ds_bpermute_b32 v89, v129, v88
	ds_bpermute_b32 v81, v129, v80
	ds_bpermute_b32 v73, v129, v72
	ds_bpermute_b32 v65, v129, v64
	ds_bpermute_b32 v57, v129, v56
	ds_bpermute_b32 v49, v129, v48
	ds_bpermute_b32 v41, v129, v40
	ds_bpermute_b32 v33, v129, v32
	ds_bpermute_b32 v25, v129, v24
	ds_bpermute_b32 v17, v129, v16
	ds_bpermute_b32 v3, v129, v2
	ds_bpermute_b32 v1, v129, v0
	s_cmp_gt_i32 s34, 7
	v_cvt_pk_bf16_f32 v4, v4, v5
	v_cvt_pk_bf16_f32 v5, v6, v7
	v_cvt_pk_bf16_f32 v6, v10, v11
	v_cvt_pk_bf16_f32 v7, v8, v9
	global_store_dwordx4 v[18:19], v[4:7], off offset:256 sc1
	s_cbranch_scc1 .LBB0_157
	s_waitcnt lgkmcnt(0)
	v_add_f32_e32 v4, v120, v121
	v_add_f32_e32 v5, v104, v105
	v_max3_f32 v4, v4, 0, v5
	v_add_f32_e32 v5, v88, v89
	v_add_f32_e32 v6, v72, v73
	v_max3_f32 v4, v4, v5, v6
	v_add_f32_e32 v5, v56, v57
	v_add_f32_e32 v6, v40, v41
	v_add_f32_e32 v2, v2, v3
	v_mbcnt_lo_u32_b32 v3, -1, 0
	v_mbcnt_hi_u32_b32 v3, -1, v3
	v_max3_f32 v4, v4, v5, v6
	v_add_f32_e32 v5, v24, v25
	v_lshlrev_b32_e32 v3, 2, v3
	v_max3_f32 v2, v4, v5, v2
	v_xor_b32_e32 v3, 4, v3
	ds_bpermute_b32 v3, v3, v2
	s_lshl_b32 s3, s14, 5
	s_waitcnt lgkmcnt(0)
	v_max_f32_e32 v3, v3, v3
	v_max_f32_e32 v2, v2, v3
	v_mbcnt_lo_u32_b32 v3, -1, 0
	v_mbcnt_hi_u32_b32 v3, -1, v3
	s_nop 0
	v_lshlrev_b32_e32 v3, 2, v3
	v_xor_b32_e32 v3, 8, v3
	ds_bpermute_b32 v3, v3, v2
	s_waitcnt lgkmcnt(0)
	v_max_f32_e32 v3, v3, v3
	v_max_f32_e32 v2, v2, v3
	v_mbcnt_lo_u32_b32 v3, -1, 0
	v_mbcnt_hi_u32_b32 v3, -1, v3
	s_nop 0
	v_lshlrev_b32_e32 v3, 2, v3
	v_xor_b32_e32 v3, 16, v3
	ds_bpermute_b32 v3, v3, v2
	s_waitcnt lgkmcnt(0)
	v_max_f32_e32 v3, v3, v3
	v_max_f32_e32 v2, v2, v3
	v_mbcnt_lo_u32_b32 v3, -1, 0
	v_mbcnt_hi_u32_b32 v3, -1, v3
	s_nop 0
	v_lshlrev_b32_e32 v3, 2, v3
	v_xor_b32_e32 v3, 32, v3
	ds_bpermute_b32 v3, v3, v2
	s_and_saveexec_b64 s[14:15], vcc
	s_cbranch_execz .LBB0_168
	s_waitcnt lgkmcnt(0)
	v_max_f32_e32 v3, v3, v3
	v_max_f32_e32 v2, v2, v2
	s_mov_b64 s[4:5], exec
	v_max_f32_e32 v2, v2, v3
	s_mov_b32 s9, 0

.LBB0_254:
	s_and_b64 vcc, exec, s[8:9]
	s_cbranch_vccz .LBB0_354
	v_readlane_b32 s24, v255, 28
	v_readlane_b32 s8, v251, 0
	s_lshr_b32 s0, s24, 1
	v_readlane_b32 s9, v251, 1
	v_readlane_b32 s10, v251, 2
	v_readlane_b32 s11, v251, 3
	v_readlane_b32 s12, v251, 4
	v_readlane_b32 s13, v251, 5
	v_readlane_b32 s14, v251, 6
	v_readlane_b32 s15, v251, 7
	v_readlane_b32 s16, v251, 8
	v_readlane_b32 s17, v251, 9
	s_cmp_eq_u32 s24, 0
	v_readlane_b32 s18, v251, 10
	v_readlane_b32 s19, v251, 11
	v_readlane_b32 s20, v251, 12
	v_readlane_b32 s21, v251, 13
	s_mov_b64 s[8:9], s[12:13]
	s_cselect_b64 vcc, -1, 0
	s_lshl_b64 s[4:5], s[0:1], 10
	s_mov_b64 s[10:11], s[14:15]
	v_mov_b32_e32 v0, 0x3ef1014c
	s_waitcnt lgkmcnt(0)
	v_mov_b32_e32 v1, 0x3e4ccccd
	s_add_u32 s8, s10, s4
	v_cndmask_b32_e32 v0, v0, v1, vcc
	s_addc_u32 s9, s11, s5
	v_lshlrev_b32_e32 v1, 2, v157
	global_load_dword v2, v1, s[8:9]
	global_load_dword v3, v1, s[8:9] offset:256
	v_mbcnt_lo_u32_b32 v5, -1, 0
	v_mbcnt_hi_u32_b32 v5, -1, v5
	s_mov_b32 s3, 0x3fb8aa3b
	v_lshlrev_b32_e32 v5, 2, v5
	v_xor_b32_e32 v5, 4, v5
	s_mov_b32 s4, 0xc2ce8ed0
	s_mov_b32 s5, 0x42b17218
	v_mov_b32_e32 v6, 0x7f800000
	s_mov_b64 s[12:13], s[16:17]
	s_mov_b64 s[14:15], s[18:19]
	s_mov_b64 s[16:17], s[20:21]
	v_readlane_b32 s44, v252, 36
	v_readlane_b32 s10, v252, 34
	v_readlane_b32 s11, v252, 35
	v_and_b32_e32 v148, 31, v138
	v_sub_f32_e32 v151, 1.0, v0
	v_lshlrev_b32_e32 v164, 7, v148
	v_readlane_b32 s43, v252, 50
	v_readlane_b32 s45, v252, 53
	v_readlane_b32 s46, v252, 55
	v_readlane_b32 s47, v252, 38
	v_readlane_b32 s48, v252, 39
	v_readlane_b32 s49, v252, 40
	v_readlane_b32 s50, v252, 42
	v_readlane_b32 s51, v252, 41
	v_readlane_b32 s77, v252, 43
	v_readlane_b32 s78, v252, 49
	v_readlane_b32 s25, v255, 29
	v_readlane_b32 s22, v251, 14
	v_readlane_b32 s23, v251, 15
	s_waitcnt vmcnt(0)
	v_mul_f32_e32 v4, v2, v3
	ds_bpermute_b32 v4, v5, v4
	s_waitcnt lgkmcnt(0)
	v_fmac_f32_e32 v4, v2, v3
	v_mbcnt_lo_u32_b32 v2, -1, 0
	v_mbcnt_hi_u32_b32 v2, -1, v2
	v_mbcnt_lo_u32_b32 v3, -1, 0
	v_mbcnt_hi_u32_b32 v3, -1, v3
	s_nop 0
	v_lshlrev_b32_e32 v2, 2, v2
	v_xor_b32_e32 v2, 8, v2
	ds_bpermute_b32 v2, v2, v4
	v_lshlrev_b32_e32 v3, 2, v3
	v_xor_b32_e32 v3, 16, v3
	s_waitcnt lgkmcnt(0)
	v_add_f32_e32 v2, v4, v2
	ds_bpermute_b32 v3, v3, v2
	s_waitcnt lgkmcnt(0)
	v_add_f32_e32 v2, v2, v3
	v_mbcnt_lo_u32_b32 v3, -1, 0
	v_mbcnt_hi_u32_b32 v3, -1, v3
	s_nop 0
	v_lshlrev_b32_e32 v3, 2, v3
	v_xor_b32_e32 v3, 32, v3
	ds_bpermute_b32 v3, v3, v2
	s_waitcnt lgkmcnt(0)
	v_add_f32_e32 v2, v2, v3
	v_mbcnt_lo_u32_b32 v3, -1, 0
	v_mbcnt_hi_u32_b32 v3, -1, v3
	s_nop 0
	v_lshlrev_b32_e32 v3, 2, v3
	v_xor_b32_e32 v3, 64, v3
	ds_bpermute_b32 v3, v3, v2
	s_waitcnt lgkmcnt(0)
	v_add_f32_e32 v2, v2, v3
	v_mbcnt_lo_u32_b32 v3, -1, 0
	v_mbcnt_hi_u32_b32 v3, -1, v3
	s_nop 0
	v_lshlrev_b32_e32 v3, 2, v3
	v_xor_b32_e32 v3, 0x80, v3
	ds_bpermute_b32 v3, v3, v2
	s_waitcnt lgkmcnt(0)
	v_add_f32_e32 v2, v2, v3
	v_mul_f32_e32 v3, 0x3fb8aa3b, v2
	v_fma_f32 v4, v2, s3, -v3
	v_rndne_f32_e32 v5, v3
	v_fmac_f32_e32 v4, 0x32a5705f, v2
	v_sub_f32_e32 v3, v3, v5
	v_add_f32_e32 v3, v3, v4
	v_exp_f32_e32 v3, v3
	v_cvt_i32_f32_e32 v4, v5
	v_cmp_ngt_f32_e32 vcc, s4, v2
	v_ldexp_f32 v3, v3, v4
	s_nop 0
	v_cndmask_b32_e32 v3, 0, v3, vcc
	v_cmp_nlt_f32_e32 vcc, s5, v2
	s_nop 1
	v_cndmask_b32_e32 v2, v6, v3, vcc
	global_load_dword v3, v1, s[8:9] offset:512
	s_nop 0
	global_load_dword v1, v1, s[8:9] offset:768
	v_mbcnt_lo_u32_b32 v5, -1, 0
	v_mbcnt_hi_u32_b32 v5, -1, v5
	v_cmp_eq_u32_e64 s[8:9], 0, v138
	v_lshlrev_b32_e32 v5, 2, v5
	v_xor_b32_e32 v5, 4, v5
	s_waitcnt vmcnt(0)
	v_mul_f32_e32 v4, v3, v1
	ds_bpermute_b32 v4, v5, v4
	s_waitcnt lgkmcnt(0)
	v_fmac_f32_e32 v4, v3, v1
	v_mbcnt_lo_u32_b32 v1, -1, 0
	v_mbcnt_hi_u32_b32 v1, -1, v1
	v_mbcnt_lo_u32_b32 v3, -1, 0
	v_mbcnt_hi_u32_b32 v3, -1, v3
	s_nop 0
	v_lshlrev_b32_e32 v1, 2, v1
	v_xor_b32_e32 v1, 8, v1
	ds_bpermute_b32 v1, v1, v4
	v_lshlrev_b32_e32 v3, 2, v3
	v_xor_b32_e32 v3, 16, v3
	s_waitcnt lgkmcnt(0)
	v_add_f32_e32 v1, v4, v1
	ds_bpermute_b32 v3, v3, v1
	s_waitcnt lgkmcnt(0)
	v_add_f32_e32 v1, v1, v3
	v_mbcnt_lo_u32_b32 v3, -1, 0
	v_mbcnt_hi_u32_b32 v3, -1, v3
	s_nop 0
	v_lshlrev_b32_e32 v3, 2, v3
	v_xor_b32_e32 v3, 32, v3
	ds_bpermute_b32 v3, v3, v1
	s_waitcnt lgkmcnt(0)
	v_add_f32_e32 v1, v1, v3
	v_mbcnt_lo_u32_b32 v3, -1, 0
	v_mbcnt_hi_u32_b32 v3, -1, v3
	s_nop 0
	v_lshlrev_b32_e32 v3, 2, v3
	v_xor_b32_e32 v3, 64, v3
	ds_bpermute_b32 v3, v3, v1
	s_waitcnt lgkmcnt(0)
	v_add_f32_e32 v1, v1, v3
	v_mbcnt_lo_u32_b32 v3, -1, 0
	v_mbcnt_hi_u32_b32 v3, -1, v3
	s_nop 0
	v_lshlrev_b32_e32 v3, 2, v3
	v_xor_b32_e32 v3, 0x80, v3
	ds_bpermute_b32 v3, v3, v1
	s_waitcnt lgkmcnt(0)
	v_add_f32_e32 v1, v1, v3
	v_mul_f32_e32 v3, 0x3fb8aa3b, v1
	v_fma_f32 v4, v1, s3, -v3
	v_rndne_f32_e32 v5, v3
	v_fmac_f32_e32 v4, 0x32a5705f, v1
	v_sub_f32_e32 v3, v3, v5
	v_add_f32_e32 v3, v3, v4
	v_exp_f32_e32 v3, v3
	v_cvt_i32_f32_e32 v4, v5
	v_cmp_ngt_f32_e32 vcc, s4, v1
	v_readlane_b32 s3, v251, 50
	v_lshrrev_b32_e32 v5, 2, v138
	v_ldexp_f32 v3, v3, v4
	v_cndmask_b32_e32 v3, 0, v3, vcc
	v_cmp_nlt_f32_e32 vcc, s5, v1
	s_lshl_b64 s[4:5], s[0:1], 9
	s_add_u32 s14, s12, s4
	s_addc_u32 s15, s13, s5
	s_lshl_b32 s0, s24, 8
	s_lshl_b64 s[4:5], s[0:1], 2
	s_add_u32 s4, s3, s4
	v_readlane_b32 s3, v251, 51
	s_addc_u32 s5, s3, s5
	s_lshl_b32 s3, s24, 2
	s_add_i32 s6, s3, s44
	s_lshl_b32 s6, s6, 6
	v_cndmask_b32_e32 v1, v6, v3, vcc
	s_ashr_i32 s7, s6, 31
	v_sub_f32_e32 v1, v2, v1
	v_lshlrev_b32_e32 v2, 3, v157
	s_lshl_b64 s[6:7], s[6:7], 2
	v_and_b32_e32 v150, 24, v2
	v_lshrrev_b32_e32 v2, 3, v157
	s_add_u32 s16, s10, s6
	v_readlane_b32 s6, v252, 37
	v_xor_b32_e32 v4, v2, v157
	s_addc_u32 s17, s11, s7
	s_add_i32 s3, s3, s6
	v_lshrrev_b32_e32 v3, 5, v157
	v_lshlrev_b32_e32 v4, 3, v4
	s_lshl_b32 s6, s3, 6
	v_and_b32_e32 v152, 56, v4
	v_lshlrev_b32_e32 v4, 2, v3
	s_ashr_i32 s7, s6, 31
	v_add_f32_e32 v149, v0, v1
	v_lshlrev_b32_e32 v0, 3, v3
	v_lshrrev_b32_e32 v1, 2, v157
	v_sub_u32_e32 v153, v148, v4
	v_and_or_b32 v4, v5, 3, v4
	v_lshlrev_b32_e32 v5, 1, v157
	v_bitop3_b32 v3, v3, v138, 7 bitop3:0x78
	s_lshl_b64 s[6:7], s[6:7], 2
	v_readlane_b32 s3, v252, 16
	v_lshlrev_b32_e32 v4, 6, v4
	v_and_b32_e32 v5, 32, v5
	v_lshlrev_b32_e32 v163, 4, v3
	s_add_u32 s18, s10, s6
	v_or_b32_e32 v168, s3, v1
	v_readlane_b32 s3, v252, 18
	v_or3_b32 v162, v5, v4, v150
	v_xor_b32_e32 v165, 32, v163
	v_xor_b32_e32 v166, 64, v163
	v_xor_b32_e32 v167, 0x60, v163
	s_addc_u32 s19, s11, s7
	v_or_b32_e32 v169, s3, v2
	v_lshlrev_b32_e32 v154, 1, v0
	v_cmp_gt_u32_e32 vcc, 0x80, v138
	s_and_saveexec_b64 s[10:11], vcc
	v_lshlrev_b32_e32 v0, 2, v138
	global_load_dword v1, v0, s[14:15]
	v_add_u32_e32 v0, 0x20340, v0
	s_waitcnt vmcnt(0)
	ds_write_b32 v0, v1
	s_waitcnt lgkmcnt(0)
	s_or_b64 exec, exec, s[10:11]
	s_branch .LBB0_258

.LBB0_319:
	s_add_i32 s6, s39, 0xfffe8000
	s_and_b32 s6, s6, 0x18000
	s_add_i32 s12, s6, 0
	s_add_i32 s6, s12, s40
	v_add_u32_e32 v76, s6, v164
	s_lshl_b32 s6, s3, 6
	v_cvt_f32_i32_e32 v80, s6
	v_add_u32_e32 v68, v76, v163
	v_add_u32_e32 v72, v76, v165
	v_add_u32_e32 v77, v76, v166
	v_add_u32_e32 v81, v76, v167
	ds_read_b128 v[64:67], v68
	ds_read_b128 v[114:117], v68 offset:4096
	ds_read_b128 v[68:71], v72
	ds_read_b128 v[124:127], v72 offset:4096
	ds_read_b128 v[72:75], v77
	ds_read_b128 v[134:137], v77 offset:4096
	ds_read_b128 v[76:79], v81
	ds_read_b128 v[120:123], v81 offset:4096
	s_cmp_lt_i32 s3, s24
	s_cselect_b64 s[6:7], -1, 0
	v_sub_f32_e32 v113, v170, v80
	v_cndmask_b32_e64 v118, -v156, v156, s[6:7]
	v_mul_f32_e32 v119, 0x41000000, v118
	v_fma_f32 v80, v118, -v113, -v155
	v_add_f32_e32 v84, v119, v80
	v_add_f32_e32 v81, v118, v80
	v_add_f32_e32 v88, v119, v84
	v_add_f32_e32 v82, v118, v81
	v_add_f32_e32 v85, v118, v84
	v_add_f32_e32 v92, v119, v88
	v_add_f32_e32 v83, v118, v82
	v_add_f32_e32 v86, v118, v85
	v_add_f32_e32 v89, v118, v88
	v_add_f32_e32 v87, v118, v86
	v_add_f32_e32 v90, v118, v89
	v_add_f32_e32 v93, v118, v92
	v_add_f32_e32 v91, v118, v90
	v_add_f32_e32 v94, v118, v93
	v_add_f32_e32 v95, v118, v94
	s_nop 1
	s_waitcnt lgkmcnt(7)
	v_mfma_f32_32x32x16_bf16 v[80:95], v[64:67], v[96:99], v[80:95]
	v_sub_f32_e32 v64, 0x42000000, v113
	v_fma_f32 v64, v118, v64, -v155
	v_add_f32_e32 v65, v118, v64
	v_add_u32_e32 v132, s12, v162
	v_add_f32_e32 v66, v118, v65
	v_add_f32_e32 v67, v118, v66
	s_waitcnt lgkmcnt(5)
	v_mfma_f32_32x32x16_bf16 v[80:95], v[68:71], v[100:103], v[80:95]
	v_add_f32_e32 v68, v119, v64
	v_add_f32_e32 v69, v118, v68
	v_add_f32_e32 v70, v118, v69
	v_add_f32_e32 v71, v118, v70
	s_waitcnt lgkmcnt(3)
	v_mfma_f32_32x32x16_bf16 v[80:95], v[72:75], v[104:107], v[80:95]
	v_add_f32_e32 v72, v119, v68
	v_add_f32_e32 v73, v118, v72
	v_add_f32_e32 v74, v118, v73
	v_add_f32_e32 v75, v118, v74
	s_waitcnt lgkmcnt(1)
	v_mfma_f32_32x32x16_bf16 v[80:95], v[76:79], v[108:111], v[80:95]
	v_add_f32_e32 v76, v119, v72
	v_add_f32_e32 v77, v118, v76
	v_add_f32_e32 v78, v118, v77
	v_add_f32_e32 v79, v118, v78
	s_nop 1
	s_nop 7
	v_exp_f32_e32 v80, v80
	ds_read_b64_tr_b16 v[138:139], v132 offset:16384
	ds_read_b64_tr_b16 v[140:141], v132 offset:16896
	ds_read_b64_tr_b16 v[142:143], v132 offset:17408
	ds_read_b64_tr_b16 v[144:145], v132 offset:17920
	v_exp_f32_e32 v81, v81
	v_exp_f32_e32 v82, v82
	v_exp_f32_e32 v83, v83
	v_add_f32_e32 v112, v112, v80
	v_add_f32_e32 v112, v81, v112
	v_add_f32_e32 v112, v82, v112
	v_add_f32_e32 v112, v83, v112
	v_mfma_f32_32x32x16_bf16 v[64:79], v[114:117], v[96:99], v[64:79]
	ds_read_b64_tr_b16 v[158:159], v132 offset:20480
	ds_read_b64_tr_b16 v[160:161], v132 offset:20992
	ds_read_b64_tr_b16 v[172:173], v132 offset:21504
	ds_read_b64_tr_b16 v[174:175], v132 offset:22016
	v_exp_f32_e32 v133, v84
	v_exp_f32_e32 v146, v85
	v_exp_f32_e32 v147, v86
	v_exp_f32_e32 v171, v87
	v_add_f32_e32 v84, v133, v112
	v_add_f32_e32 v84, v146, v84
	v_add_f32_e32 v84, v147, v84
	v_add_f32_e32 v84, v171, v84
	v_mfma_f32_32x32x16_bf16 v[64:79], v[124:127], v[100:103], v[64:79]
	ds_read_b64_tr_b16 v[124:125], v132 offset:24576
	ds_read_b64_tr_b16 v[126:127], v132 offset:25088
	ds_read_b64_tr_b16 v[116:117], v132 offset:25600
	ds_read_b64_tr_b16 v[118:119], v132 offset:26112
	v_exp_f32_e32 v88, v88
	v_exp_f32_e32 v89, v89
	v_exp_f32_e32 v90, v90
	v_exp_f32_e32 v91, v91
	v_add_f32_e32 v84, v88, v84
	v_add_f32_e32 v84, v89, v84
	v_add_f32_e32 v84, v90, v84
	v_add_f32_e32 v176, v91, v84
	v_mfma_f32_32x32x16_bf16 v[64:79], v[134:137], v[104:107], v[64:79]
	ds_read_b64_tr_b16 v[112:113], v132 offset:28672
	ds_read_b64_tr_b16 v[114:115], v132 offset:29184
	ds_read_b64_tr_b16 v[84:85], v132 offset:29696
	ds_read_b64_tr_b16 v[86:87], v132 offset:30208
	v_exp_f32_e32 v134, v92
	v_exp_f32_e32 v135, v93
	v_exp_f32_e32 v136, v94
	v_exp_f32_e32 v95, v95
	v_add_f32_e32 v92, v134, v176
	v_add_f32_e32 v92, v135, v92
	v_add_f32_e32 v92, v136, v92
	v_add_f32_e32 v137, v95, v92
	s_waitcnt lgkmcnt(14)
	v_mfma_f32_32x32x16_bf16 v[64:79], v[120:123], v[108:111], v[64:79]
	v_cvt_pk_bf16_f32 v120, v80, v81
	v_cvt_pk_bf16_f32 v121, v82, v83
	v_cvt_pk_bf16_f32 v122, v133, v146
	v_cvt_pk_bf16_f32 v123, v147, v171
	v_cvt_pk_bf16_f32 v92, v88, v89
	v_cvt_pk_bf16_f32 v93, v90, v91
	v_cvt_pk_bf16_f32 v94, v134, v135
	v_cvt_pk_bf16_f32 v95, v136, v95
	v_mfma_f32_32x32x16_bf16 v[0:15], v[138:141], v[120:123], v[0:15]
	ds_read_b64_tr_b16 v[80:81], v132 offset:18432
	ds_read_b64_tr_b16 v[82:83], v132 offset:18944
	s_nop 0
	v_exp_f32_e32 v133, v64
	v_exp_f32_e32 v138, v65
	v_add_f32_e32 v64, v137, v133
	v_add_f32_e32 v64, v138, v64
	s_waitcnt lgkmcnt(14)
	v_mfma_f32_32x32x16_bf16 v[0:15], v[142:145], v[92:95], v[0:15]
	ds_read_b64_tr_b16 v[88:89], v132 offset:19456
	ds_read_b64_tr_b16 v[90:91], v132 offset:19968
	v_exp_f32_e32 v139, v66
	v_exp_f32_e32 v140, v67
	v_add_f32_e32 v64, v139, v64
	v_add_f32_e32 v134, v140, v64
	s_waitcnt lgkmcnt(14)
	v_mfma_f32_32x32x16_bf16 v[16:31], v[158:161], v[120:123], v[16:31]
	ds_read_b64_tr_b16 v[64:65], v132 offset:22528
	ds_read_b64_tr_b16 v[66:67], v132 offset:23040
	v_exp_f32_e32 v141, v68
	v_exp_f32_e32 v142, v69
	v_add_f32_e32 v68, v141, v134
	v_add_f32_e32 v68, v142, v68
	s_waitcnt lgkmcnt(14)
	v_mfma_f32_32x32x16_bf16 v[16:31], v[172:175], v[92:95], v[16:31]
	ds_read_b64_tr_b16 v[134:135], v132 offset:23552
	ds_read_b64_tr_b16 v[136:137], v132 offset:24064
	v_exp_f32_e32 v143, v70
	v_exp_f32_e32 v144, v71
	v_add_f32_e32 v68, v143, v68
	v_add_f32_e32 v145, v144, v68
	s_waitcnt lgkmcnt(14)
	v_mfma_f32_32x32x16_bf16 v[32:47], v[124:127], v[120:123], v[32:47]
	ds_read_b64_tr_b16 v[68:69], v132 offset:26624
	ds_read_b64_tr_b16 v[70:71], v132 offset:27136
	v_exp_f32_e32 v124, v72
	v_exp_f32_e32 v125, v73
	v_add_f32_e32 v72, v124, v145
	v_add_f32_e32 v72, v125, v72
	s_waitcnt lgkmcnt(14)
	v_mfma_f32_32x32x16_bf16 v[32:47], v[116:119], v[92:95], v[32:47]
	ds_read_b64_tr_b16 v[116:117], v132 offset:27648
	ds_read_b64_tr_b16 v[118:119], v132 offset:28160
	v_exp_f32_e32 v126, v74
	v_exp_f32_e32 v127, v75
	v_add_f32_e32 v72, v126, v72
	v_add_f32_e32 v145, v127, v72
	s_waitcnt lgkmcnt(14)
	v_mfma_f32_32x32x16_bf16 v[48:63], v[112:115], v[120:123], v[48:63]
	ds_read_b64_tr_b16 v[72:73], v132 offset:30720
	ds_read_b64_tr_b16 v[74:75], v132 offset:31232
	v_exp_f32_e32 v113, v76
	v_exp_f32_e32 v114, v77
	v_add_f32_e32 v76, v113, v145
	v_add_f32_e32 v76, v114, v76
	s_waitcnt lgkmcnt(14)
	v_mfma_f32_32x32x16_bf16 v[48:63], v[84:87], v[92:95], v[48:63]
	v_exp_f32_e32 v95, v78
	ds_read_b64_tr_b16 v[84:85], v132 offset:31744
	ds_read_b64_tr_b16 v[86:87], v132 offset:32256
	v_exp_f32_e32 v115, v79
	v_add_f32_e32 v76, v95, v76
	v_add_f32_e32 v112, v115, v76
	v_cvt_pk_bf16_f32 v76, v133, v138
	v_cvt_pk_bf16_f32 v77, v139, v140
	v_cvt_pk_bf16_f32 v78, v141, v142
	v_cvt_pk_bf16_f32 v79, v143, v144
	v_cvt_pk_bf16_f32 v92, v124, v125
	v_cvt_pk_bf16_f32 v93, v126, v127
	v_cvt_pk_bf16_f32 v94, v113, v114
	v_cvt_pk_bf16_f32 v95, v95, v115
	s_setprio 0
	s_bitcmp1_b32 s26, 0
	s_cbranch_scc1 .Lda_dplain
	s_cmp_ge_i32 s26, s34
	s_cbranch_scc1 .Lda_dplain
	s_add_i32 s100, s26, 2
	s_and_b32 s100, s100, 3
	s_lshl_b32 s100, s100, 15
	s_add_i32 s101, s100, s43
	s_waitcnt lgkmcnt(14)
	v_mfma_f32_32x32x16_bf16 v[0:15], v[80:83], v[76:79], v[0:15]
	s_mov_b32 m0, s101
	s_addk_i32 s101, 0x2000
	global_load_lds_dwordx4 v[186:187], off
	s_waitcnt lgkmcnt(10)
	v_mfma_f32_32x32x16_bf16 v[16:31], v[64:67], v[76:79], v[16:31]
	s_mov_b32 m0, s101
	s_add_i32 s101, s100, s45
	global_load_lds_dwordx4 v[188:189], off
	s_waitcnt lgkmcnt(6)
	v_mfma_f32_32x32x16_bf16 v[32:47], v[68:71], v[76:79], v[32:47]
	s_mov_b32 m0, s101
	s_add_i32 s101, s100, s46
	global_load_lds_dwordx4 v[190:191], off
	s_waitcnt lgkmcnt(2)
	v_mfma_f32_32x32x16_bf16 v[48:63], v[72:75], v[76:79], v[48:63]
	s_mov_b32 m0, s101
	s_add_i32 s100, s100, 0x8000
	global_load_lds_dwordx4 v[192:193], off
	s_add_i32 s101, s100, s43
	v_mfma_f32_32x32x16_bf16 v[0:15], v[88:91], v[92:95], v[0:15]
	s_mov_b32 m0, s101
	s_addk_i32 s101, 0x2000
	global_load_lds_dwordx4 v[194:195], off
	v_mfma_f32_32x32x16_bf16 v[16:31], v[134:137], v[92:95], v[16:31]
	s_mov_b32 m0, s101
	s_add_i32 s101, s100, s45
	global_load_lds_dwordx4 v[196:197], off
	v_mfma_f32_32x32x16_bf16 v[32:47], v[116:119], v[92:95], v[32:47]
	s_mov_b32 m0, s101
	s_add_i32 s101, s100, s46
	global_load_lds_dwordx4 v[198:199], off
	s_waitcnt lgkmcnt(0)
	v_mfma_f32_32x32x16_bf16 v[48:63], v[84:87], v[92:95], v[48:63]
	s_mov_b32 m0, s101
	s_nop 0
	global_load_lds_dwordx4 v[200:201], off
	s_branch .Lda_dend

.Lda_tile:
	v_readlane_b32 s3, v177, s26
	s_lshr_b32 s101, s95, 8
	s_xor_b32 s101, s101, s26
	s_bitcmp1_b32 s101, 0
	s_cbranch_scc1 .Lda_p1
	s_setprio 0
	s_branch .LBB0_319
.Lda_p1:
	s_setprio 1
	s_setprio 1
	s_branch .LBB0_319

.LBB0_352:
	v_readlane_b32 s6, v252, 46
	v_readlane_b32 s7, v252, 47
	s_andn2_b64 vcc, exec, s[6:7]
	s_waitcnt lgkmcnt(0)
	s_barrier
	s_cbranch_vccnz .LBB0_256
	ds_read2_b32 v[64:65], v95 offset0:114 offset1:115
	ds_read2_b32 v[70:71], v95 offset0:120 offset1:121
	ds_read2_b32 v[72:73], v95 offset0:122 offset1:123
	ds_read2_b32 v[96:97], v95 offset0:112 offset1:113
	v_lshlrev_b32_e32 v68, 2, v67
	v_ashrrev_i32_e32 v69, 31, v68
	v_readlane_b32 s6, v253, 16
	s_waitcnt lgkmcnt(3)
	v_pk_fma_f32 v[58:59], v[58:59], v[66:67], v[64:65] op_sel_hi:[1,0,1] neg_lo:[0,0,1] neg_hi:[0,0,1]
	s_waitcnt lgkmcnt(2)
	v_pk_fma_f32 v[64:65], v[60:61], v[66:67], v[70:71] op_sel_hi:[1,0,1] neg_lo:[0,0,1] neg_hi:[0,0,1]
	s_waitcnt lgkmcnt(1)
	v_pk_fma_f32 v[60:61], v[62:63], v[66:67], v[72:73] op_sel_hi:[1,0,1] neg_lo:[0,0,1] neg_hi:[0,0,1]
	ds_read2_b32 v[70:71], v95 offset0:10 offset1:11
	ds_read2_b32 v[72:73], v95 offset0:8 offset1:9
	v_lshlrev_b32_e32 v62, 2, v68
	v_add_u32_e32 v62, 0x20340, v62
	v_pk_mul_f32 v[98:99], v[58:59], v[58:59]
	v_pk_mul_f32 v[100:101], v[64:65], v[64:65]
	s_waitcnt lgkmcnt(1)
	v_pk_fma_f32 v[86:87], v[6:7], v[66:67], v[70:71] op_sel_hi:[1,0,1] neg_lo:[0,0,1] neg_hi:[0,0,1]
	ds_read2_b32 v[6:7], v95 offset0:2 offset1:3
	s_waitcnt lgkmcnt(1)
	v_pk_fma_f32 v[88:89], v[4:5], v[66:67], v[72:73] op_sel_hi:[1,0,1] neg_lo:[0,0,1] neg_hi:[0,0,1]
	ds_read2_b32 v[4:5], v95 offset1:1
	v_pk_mul_f32 v[106:107], v[88:89], v[88:89]
	v_pk_mul_f32 v[104:105], v[86:87], v[86:87]
	s_waitcnt lgkmcnt(1)
	v_pk_fma_f32 v[90:91], v[2:3], v[66:67], v[6:7] op_sel_hi:[1,0,1] neg_lo:[0,0,1] neg_hi:[0,0,1]
	ds_read2_b32 v[2:3], v95 offset0:26 offset1:27
	s_waitcnt lgkmcnt(1)
	v_pk_fma_f32 v[92:93], v[0:1], v[66:67], v[4:5] op_sel_hi:[1,0,1] neg_lo:[0,0,1] neg_hi:[0,0,1]
	ds_read2_b32 v[0:1], v95 offset0:24 offset1:25
	v_pk_mul_f32 v[110:111], v[92:93], v[92:93]
	v_pk_mul_f32 v[108:109], v[90:91], v[90:91]
	s_waitcnt lgkmcnt(1)
	v_pk_fma_f32 v[78:79], v[14:15], v[66:67], v[2:3] op_sel_hi:[1,0,1] neg_lo:[0,0,1] neg_hi:[0,0,1]
	ds_read2_b32 v[2:3], v95 offset0:18 offset1:19
	s_waitcnt lgkmcnt(1)
	v_pk_fma_f32 v[80:81], v[12:13], v[66:67], v[0:1] op_sel_hi:[1,0,1] neg_lo:[0,0,1] neg_hi:[0,0,1]
	ds_read2_b32 v[0:1], v95 offset0:16 offset1:17
	v_pk_mul_f32 v[114:115], v[80:81], v[80:81]
	v_pk_mul_f32 v[112:113], v[78:79], v[78:79]
	s_waitcnt lgkmcnt(1)
	v_pk_fma_f32 v[82:83], v[10:11], v[66:67], v[2:3] op_sel_hi:[1,0,1] neg_lo:[0,0,1] neg_hi:[0,0,1]
	ds_read2_b32 v[2:3], v95 offset0:42 offset1:43
	s_waitcnt lgkmcnt(1)
	v_pk_fma_f32 v[84:85], v[8:9], v[66:67], v[0:1] op_sel_hi:[1,0,1] neg_lo:[0,0,1] neg_hi:[0,0,1]
	ds_read2_b32 v[0:1], v95 offset0:40 offset1:41
	v_pk_mul_f32 v[118:119], v[84:85], v[84:85]
	v_pk_mul_f32 v[116:117], v[82:83], v[82:83]
	s_waitcnt lgkmcnt(1)
	v_pk_fma_f32 v[70:71], v[22:23], v[66:67], v[2:3] op_sel_hi:[1,0,1] neg_lo:[0,0,1] neg_hi:[0,0,1]
	ds_read2_b32 v[2:3], v95 offset0:34 offset1:35
	s_waitcnt lgkmcnt(1)
	v_pk_fma_f32 v[72:73], v[20:21], v[66:67], v[0:1] op_sel_hi:[1,0,1] neg_lo:[0,0,1] neg_hi:[0,0,1]
	ds_read2_b32 v[0:1], v95 offset0:32 offset1:33
	v_pk_mul_f32 v[122:123], v[72:73], v[72:73]
	v_pk_mul_f32 v[120:121], v[70:71], v[70:71]
	s_waitcnt lgkmcnt(1)
	v_pk_fma_f32 v[74:75], v[18:19], v[66:67], v[2:3] op_sel_hi:[1,0,1] neg_lo:[0,0,1] neg_hi:[0,0,1]
	ds_read2_b32 v[2:3], v95 offset0:58 offset1:59
	s_waitcnt lgkmcnt(1)
	v_pk_fma_f32 v[76:77], v[16:17], v[66:67], v[0:1] op_sel_hi:[1,0,1] neg_lo:[0,0,1] neg_hi:[0,0,1]
	ds_read2_b32 v[0:1], v95 offset0:56 offset1:57
	v_pk_mul_f32 v[126:127], v[76:77], v[76:77]
	v_pk_mul_f32 v[124:125], v[74:75], v[74:75]
	s_waitcnt lgkmcnt(1)
	v_pk_fma_f32 v[30:31], v[30:31], v[66:67], v[2:3] op_sel_hi:[1,0,1] neg_lo:[0,0,1] neg_hi:[0,0,1]
	ds_read2_b32 v[2:3], v95 offset0:50 offset1:51
	s_waitcnt lgkmcnt(1)
	v_pk_fma_f32 v[28:29], v[28:29], v[66:67], v[0:1] op_sel_hi:[1,0,1] neg_lo:[0,0,1] neg_hi:[0,0,1]
	ds_read2_b32 v[0:1], v95 offset0:48 offset1:49
	v_pk_mul_f32 v[130:131], v[28:29], v[28:29]
	v_pk_mul_f32 v[128:129], v[30:31], v[30:31]
	s_waitcnt lgkmcnt(1)
	v_pk_fma_f32 v[26:27], v[26:27], v[66:67], v[2:3] op_sel_hi:[1,0,1] neg_lo:[0,0,1] neg_hi:[0,0,1]
	ds_read2_b32 v[2:3], v95 offset0:74 offset1:75
	s_waitcnt lgkmcnt(1)
	v_pk_fma_f32 v[68:69], v[24:25], v[66:67], v[0:1] op_sel_hi:[1,0,1] neg_lo:[0,0,1] neg_hi:[0,0,1]
	ds_read2_b32 v[0:1], v95 offset0:72 offset1:73
	v_pk_mul_f32 v[134:135], v[68:69], v[68:69]
	v_pk_mul_f32 v[132:133], v[26:27], v[26:27]
	s_waitcnt lgkmcnt(1)
	v_pk_fma_f32 v[18:19], v[38:39], v[66:67], v[2:3] op_sel_hi:[1,0,1] neg_lo:[0,0,1] neg_hi:[0,0,1]
	ds_read2_b32 v[2:3], v95 offset0:66 offset1:67
	s_waitcnt lgkmcnt(1)
	v_pk_fma_f32 v[20:21], v[36:37], v[66:67], v[0:1] op_sel_hi:[1,0,1] neg_lo:[0,0,1] neg_hi:[0,0,1]
	v_add_f32_e32 v36, v110, v111
	v_add_f32_e32 v36, v36, v108
	v_add_f32_e32 v36, v36, v109
	v_add_f32_e32 v36, v36, v106
	v_add_f32_e32 v36, v36, v107
	v_add_f32_e32 v36, v36, v104
	v_add_f32_e32 v36, v36, v105
	v_add_f32_e32 v36, v36, v118
	v_add_f32_e32 v36, v36, v119
	v_add_f32_e32 v36, v36, v116
	v_add_f32_e32 v36, v36, v117
	ds_read2_b32 v[0:1], v95 offset0:64 offset1:65
	v_add_f32_e32 v36, v36, v114
	v_add_f32_e32 v36, v36, v115
	v_add_f32_e32 v36, v36, v112
	v_add_f32_e32 v36, v36, v113
	v_add_f32_e32 v36, v36, v126
	s_waitcnt lgkmcnt(1)
	v_pk_fma_f32 v[22:23], v[34:35], v[66:67], v[2:3] op_sel_hi:[1,0,1] neg_lo:[0,0,1] neg_hi:[0,0,1]
	ds_read2_b32 v[2:3], v95 offset0:90 offset1:91
	s_waitcnt lgkmcnt(1)
	v_pk_fma_f32 v[24:25], v[32:33], v[66:67], v[0:1] op_sel_hi:[1,0,1] neg_lo:[0,0,1] neg_hi:[0,0,1]
	ds_read2_b32 v[0:1], v95 offset0:88 offset1:89
	v_add_f32_e32 v36, v36, v127
	v_add_f32_e32 v36, v36, v124
	v_add_f32_e32 v36, v36, v125
	v_add_f32_e32 v36, v36, v122
	v_add_f32_e32 v36, v36, v123
	s_waitcnt lgkmcnt(1)
	v_pk_fma_f32 v[10:11], v[46:47], v[66:67], v[2:3] op_sel_hi:[1,0,1] neg_lo:[0,0,1] neg_hi:[0,0,1]
	ds_read2_b32 v[2:3], v95 offset0:82 offset1:83
	s_waitcnt lgkmcnt(1)
	v_pk_fma_f32 v[12:13], v[44:45], v[66:67], v[0:1] op_sel_hi:[1,0,1] neg_lo:[0,0,1] neg_hi:[0,0,1]
	ds_read2_b32 v[0:1], v95 offset0:80 offset1:81
	v_add_f32_e32 v36, v36, v120
	v_add_f32_e32 v36, v36, v121
	v_add_f32_e32 v36, v36, v134
	v_add_f32_e32 v36, v36, v135
	v_add_f32_e32 v36, v36, v132
	s_waitcnt lgkmcnt(1)
	v_pk_fma_f32 v[14:15], v[42:43], v[66:67], v[2:3] op_sel_hi:[1,0,1] neg_lo:[0,0,1] neg_hi:[0,0,1]
	ds_read2_b32 v[2:3], v95 offset0:106 offset1:107
	ds_read2_b32 v[6:7], v95 offset0:98 offset1:99
	ds_read2_b32 v[8:9], v95 offset0:96 offset1:97
	s_waitcnt lgkmcnt(3)
	v_pk_fma_f32 v[16:17], v[40:41], v[66:67], v[0:1] op_sel_hi:[1,0,1] neg_lo:[0,0,1] neg_hi:[0,0,1]
	ds_read2_b32 v[0:1], v95 offset0:104 offset1:105
	v_add_f32_e32 v36, v36, v133
	v_add_f32_e32 v36, v36, v130
	v_add_f32_e32 v36, v36, v131
	v_add_f32_e32 v36, v36, v128
	v_pk_mul_f32 v[32:33], v[24:25], v[24:25]
	v_add_f32_e32 v36, v36, v129
	s_waitcnt lgkmcnt(3)
	v_pk_fma_f32 v[2:3], v[54:55], v[66:67], v[2:3] op_sel_hi:[1,0,1] neg_lo:[0,0,1] neg_hi:[0,0,1]
	s_waitcnt lgkmcnt(0)
	v_pk_fma_f32 v[4:5], v[52:53], v[66:67], v[0:1] op_sel_hi:[1,0,1] neg_lo:[0,0,1] neg_hi:[0,0,1]
	v_pk_fma_f32 v[6:7], v[50:51], v[66:67], v[6:7] op_sel_hi:[1,0,1] neg_lo:[0,0,1] neg_hi:[0,0,1]
	v_pk_fma_f32 v[8:9], v[48:49], v[66:67], v[8:9] op_sel_hi:[1,0,1] neg_lo:[0,0,1] neg_hi:[0,0,1]
	v_pk_fma_f32 v[0:1], v[56:57], v[66:67], v[96:97] op_sel_hi:[1,0,1] neg_lo:[0,0,1] neg_hi:[0,0,1]
	v_add_f32_e32 v32, v36, v32
	v_mbcnt_lo_u32_b32 v66, -1, 0
	v_mbcnt_hi_u32_b32 v66, -1, v66
	ds_read_b128 v[36:39], v62
	ds_read_b128 v[40:43], v62 offset:32
	v_pk_mul_f32 v[34:35], v[22:23], v[22:23]
	v_add_f32_e32 v32, v32, v33
	v_add_f32_e32 v32, v32, v34
	v_pk_mul_f32 v[138:139], v[20:21], v[20:21]
	v_add_f32_e32 v32, v32, v35
	v_add_f32_e32 v32, v32, v138
	v_pk_mul_f32 v[136:137], v[18:19], v[18:19]
	v_add_f32_e32 v32, v32, v139
	v_add_f32_e32 v32, v32, v136
	v_pk_mul_f32 v[142:143], v[16:17], v[16:17]
	v_add_f32_e32 v32, v32, v137
	v_add_f32_e32 v32, v32, v142
	v_pk_mul_f32 v[140:141], v[14:15], v[14:15]
	v_add_f32_e32 v32, v32, v143
	v_add_f32_e32 v32, v32, v140
	v_pk_mul_f32 v[44:45], v[12:13], v[12:13]
	v_add_f32_e32 v32, v32, v141
	v_add_f32_e32 v32, v32, v44
	v_pk_mul_f32 v[46:47], v[10:11], v[10:11]
	v_add_f32_e32 v32, v32, v45
	v_add_f32_e32 v32, v32, v46
	v_pk_mul_f32 v[48:49], v[8:9], v[8:9]
	v_add_f32_e32 v32, v32, v47
	v_add_f32_e32 v32, v32, v48
	v_pk_mul_f32 v[50:51], v[6:7], v[6:7]
	v_add_f32_e32 v32, v32, v49
	v_add_f32_e32 v32, v32, v50
	v_pk_mul_f32 v[52:53], v[4:5], v[4:5]
	v_add_f32_e32 v32, v32, v51
	v_add_f32_e32 v32, v32, v52
	v_pk_mul_f32 v[54:55], v[2:3], v[2:3]
	v_add_f32_e32 v32, v32, v53
	v_add_f32_e32 v32, v32, v54
	v_pk_mul_f32 v[56:57], v[0:1], v[0:1]
	v_add_f32_e32 v32, v32, v55
	v_add_f32_e32 v32, v32, v56
	v_add_f32_e32 v32, v32, v57
	v_add_f32_e32 v32, v32, v98
	v_add_f32_e32 v32, v32, v99
	v_add_f32_e32 v32, v32, v100
	v_pk_mul_f32 v[102:103], v[60:61], v[60:61]
	v_add_f32_e32 v32, v32, v101
	v_add_f32_e32 v32, v32, v102
	v_add_f32_e32 v34, v32, v103
	v_lshlrev_b32_e32 v32, 2, v66
	v_xor_b32_e32 v32, 0x80, v32
	ds_bpermute_b32 v35, v32, v34
	v_or_b32_e32 v32, s30, v94
	v_mov_b32_e32 v33, s31
	v_lshlrev_b64 v[32:33], 11, v[32:33]
	v_readlane_b32 s7, v253, 17
	s_waitcnt lgkmcnt(0)
	v_add_f32_e32 v34, v34, v35
	v_fmamk_f32 v34, v34, 0x3c000000, v217
	v_mul_f32_e32 v35, 0x4f800000, v34
	v_cmp_gt_f32_e32 vcc, s79, v34
	v_lshl_add_u64 v[32:33], s[6:7], 0, v[32:33]
	v_lshl_add_u64 v[32:33], s[20:21], 1, v[32:33]
	v_cndmask_b32_e32 v34, v34, v35, vcc
	v_sqrt_f32_e32 v35, v34
	s_nop 0
	v_add_u32_e32 v44, -1, v35
	v_fma_f32 v45, -v44, v35, v34
	v_cmp_ge_f32_e64 s[10:11], 0, v45
	v_add_u32_e32 v45, 1, v35
	s_nop 0
	v_cndmask_b32_e64 v44, v35, v44, s[10:11]
	v_fma_f32 v35, -v45, v35, v34
	v_cmp_lt_f32_e64 s[10:11], 0, v35
	s_nop 1
	v_cndmask_b32_e64 v35, v44, v45, s[10:11]
	v_mul_f32_e32 v44, 0x37800000, v35
	v_cndmask_b32_e32 v35, v35, v44, vcc
	v_cmp_class_f32_e32 vcc, v34, v215
	s_nop 1
	v_cndmask_b32_e32 v44, v35, v34, vcc
	v_div_scale_f32 v45, s[6:7], v44, v44, 1.0
	v_rcp_f32_e32 v46, v45
	v_lshlrev_b32_e32 v34, 3, v67
	v_ashrrev_i32_e32 v35, 31, v34
	v_lshl_add_u64 v[32:33], v[34:35], 1, v[32:33]
	v_fma_f32 v34, -v45, v46, 1.0
	v_fmac_f32_e32 v46, v34, v46
	v_div_scale_f32 v34, vcc, 1.0, v44, 1.0
	v_mul_f32_e32 v35, v34, v46
	v_fma_f32 v47, -v45, v35, v34
	v_fmac_f32_e32 v35, v47, v46
	v_fma_f32 v34, -v45, v35, v34
	v_div_fmas_f32 v34, v34, v46, v35
	v_div_fixup_f32 v34, v34, v44, 1.0
	v_mul_f32_e32 v34, v151, v34
	v_pk_mul_f32 v[44:45], v[92:93], v[34:35] op_sel_hi:[1,0]
	v_pk_mul_f32 v[46:47], v[74:75], v[34:35] op_sel_hi:[1,0]
	s_waitcnt lgkmcnt(1)
	v_pk_mul_f32 v[36:37], v[36:37], v[44:45]
	v_pk_mul_f32 v[44:45], v[90:91], v[34:35] op_sel_hi:[1,0]
	v_cvt_pk_bf16_f32 v36, v36, v37
	v_pk_mul_f32 v[38:39], v[38:39], v[44:45]
	v_pk_mul_f32 v[44:45], v[84:85], v[34:35] op_sel_hi:[1,0]
	v_cvt_pk_bf16_f32 v37, v38, v39
	v_pk_mul_f32 v[38:39], v[88:89], v[34:35] op_sel_hi:[1,0]
	v_pk_mul_f32 v[48:49], v[72:73], v[34:35] op_sel_hi:[1,0]
	s_waitcnt lgkmcnt(0)
	v_pk_mul_f32 v[38:39], v[40:41], v[38:39]
	v_pk_mul_f32 v[40:41], v[86:87], v[34:35] op_sel_hi:[1,0]
	v_cvt_pk_bf16_f32 v38, v38, v39
	v_pk_mul_f32 v[40:41], v[42:43], v[40:41]
	s_nop 0
	v_permlane32_swap_b32_e32 v36, v38
	v_cvt_pk_bf16_f32 v39, v40, v41
	s_nop 1
	v_permlane32_swap_b32_e32 v37, v39
	global_store_dwordx4 v[32:33], v[36:39], off
	s_nop 0
	ds_read_b128 v[36:39], v62 offset:64
	s_nop 0
	ds_read_b128 v[40:43], v62 offset:96
	v_pk_mul_f32 v[50:51], v[70:71], v[34:35] op_sel_hi:[1,0]
	v_pk_mul_f32 v[26:27], v[26:27], v[34:35] op_sel_hi:[1,0]
	v_pk_mul_f32 v[28:29], v[28:29], v[34:35] op_sel_hi:[1,0]
	v_pk_mul_f32 v[30:31], v[30:31], v[34:35] op_sel_hi:[1,0]
	v_pk_mul_f32 v[24:25], v[24:25], v[34:35] op_sel_hi:[1,0]
	v_pk_mul_f32 v[22:23], v[22:23], v[34:35] op_sel_hi:[1,0]
	v_pk_mul_f32 v[20:21], v[20:21], v[34:35] op_sel_hi:[1,0]
	v_pk_mul_f32 v[18:19], v[18:19], v[34:35] op_sel_hi:[1,0]
	v_pk_mul_f32 v[16:17], v[16:17], v[34:35] op_sel_hi:[1,0]
	v_pk_mul_f32 v[14:15], v[14:15], v[34:35] op_sel_hi:[1,0]
	v_pk_mul_f32 v[12:13], v[12:13], v[34:35] op_sel_hi:[1,0]
	v_pk_mul_f32 v[10:11], v[10:11], v[34:35] op_sel_hi:[1,0]
	v_pk_mul_f32 v[8:9], v[8:9], v[34:35] op_sel_hi:[1,0]
	v_pk_mul_f32 v[6:7], v[6:7], v[34:35] op_sel_hi:[1,0]
	v_pk_mul_f32 v[4:5], v[4:5], v[34:35] op_sel_hi:[1,0]
	v_pk_mul_f32 v[2:3], v[2:3], v[34:35] op_sel_hi:[1,0]
	v_pk_mul_f32 v[0:1], v[0:1], v[34:35] op_sel_hi:[1,0]
	s_waitcnt lgkmcnt(1)
	v_pk_mul_f32 v[36:37], v[36:37], v[44:45]
	v_pk_mul_f32 v[44:45], v[82:83], v[34:35] op_sel_hi:[1,0]
	v_cvt_pk_bf16_f32 v36, v36, v37
	v_pk_mul_f32 v[38:39], v[38:39], v[44:45]
	v_pk_mul_f32 v[44:45], v[76:77], v[34:35] op_sel_hi:[1,0]
	v_cvt_pk_bf16_f32 v37, v38, v39
	v_pk_mul_f32 v[38:39], v[80:81], v[34:35] op_sel_hi:[1,0]
	s_waitcnt lgkmcnt(0)
	v_pk_mul_f32 v[38:39], v[40:41], v[38:39]
	v_pk_mul_f32 v[40:41], v[78:79], v[34:35] op_sel_hi:[1,0]
	v_cvt_pk_bf16_f32 v38, v38, v39
	v_pk_mul_f32 v[40:41], v[42:43], v[40:41]
	s_nop 0
	v_permlane32_swap_b32_e32 v36, v38
	v_cvt_pk_bf16_f32 v39, v40, v41
	s_nop 1
	v_permlane32_swap_b32_e32 v37, v39
	global_store_dwordx4 v[32:33], v[36:39], off offset:32
	s_nop 0
	ds_read_b128 v[36:39], v62 offset:128
	s_nop 0
	ds_read_b128 v[40:43], v62 offset:160
	s_waitcnt lgkmcnt(1)
	v_pk_mul_f32 v[36:37], v[44:45], v[36:37]
	v_pk_mul_f32 v[38:39], v[46:47], v[38:39]
	s_waitcnt lgkmcnt(0)
	v_pk_mul_f32 v[40:41], v[48:49], v[40:41]
	v_pk_mul_f32 v[42:43], v[50:51], v[42:43]
	v_cvt_pk_bf16_f32 v36, v36, v37
	v_cvt_pk_bf16_f32 v37, v38, v39
	v_cvt_pk_bf16_f32 v38, v40, v41
	v_cvt_pk_bf16_f32 v39, v42, v43
	s_nop 0
	v_permlane32_swap_b32_e32 v36, v38
	v_permlane32_swap_b32_e32 v37, v39
	global_store_dwordx4 v[32:33], v[36:39], off offset:64
	s_nop 0
	ds_read_b128 v[36:39], v62 offset:192
	s_nop 0
	ds_read_b128 v[40:43], v62 offset:224
	v_pk_mul_f32 v[44:45], v[68:69], v[34:35] op_sel_hi:[1,0]
	s_waitcnt lgkmcnt(1)
	v_pk_mul_f32 v[38:39], v[26:27], v[38:39]
	v_pk_mul_f32 v[36:37], v[44:45], v[36:37]
	s_waitcnt lgkmcnt(0)
	v_pk_mul_f32 v[28:29], v[28:29], v[40:41]
	v_pk_mul_f32 v[30:31], v[30:31], v[42:43]
	v_cvt_pk_bf16_f32 v26, v36, v37
	v_cvt_pk_bf16_f32 v27, v38, v39
	v_cvt_pk_bf16_f32 v28, v28, v29
	v_cvt_pk_bf16_f32 v29, v30, v31
	s_nop 0
	v_permlane32_swap_b32_e32 v26, v28
	v_permlane32_swap_b32_e32 v27, v29
	global_store_dwordx4 v[32:33], v[26:29], off offset:96
	s_nop 0
	ds_read_b128 v[26:29], v62 offset:256
	s_nop 0
	ds_read_b128 v[36:39], v62 offset:288
	s_waitcnt lgkmcnt(1)
	v_pk_mul_f32 v[24:25], v[24:25], v[26:27]
	v_pk_mul_f32 v[22:23], v[22:23], v[28:29]
	s_waitcnt lgkmcnt(0)
	v_pk_mul_f32 v[20:21], v[20:21], v[36:37]
	v_pk_mul_f32 v[26:27], v[18:19], v[38:39]
	v_cvt_pk_bf16_f32 v18, v24, v25
	v_cvt_pk_bf16_f32 v19, v22, v23
	v_cvt_pk_bf16_f32 v20, v20, v21
	v_cvt_pk_bf16_f32 v21, v26, v27
	s_nop 0
	v_permlane32_swap_b32_e32 v18, v20
	v_permlane32_swap_b32_e32 v19, v21
	global_store_dwordx4 v[32:33], v[18:21], off offset:128
	s_nop 0
	ds_read_b128 v[18:21], v62 offset:320
	s_nop 0
	ds_read_b128 v[22:25], v62 offset:352
	s_waitcnt lgkmcnt(1)
	v_pk_mul_f32 v[16:17], v[16:17], v[18:19]
	v_pk_mul_f32 v[14:15], v[14:15], v[20:21]
	s_waitcnt lgkmcnt(0)
	v_pk_mul_f32 v[12:13], v[12:13], v[22:23]
	v_pk_mul_f32 v[18:19], v[10:11], v[24:25]
	v_cvt_pk_bf16_f32 v10, v16, v17
	v_cvt_pk_bf16_f32 v11, v14, v15
	v_cvt_pk_bf16_f32 v12, v12, v13
	v_cvt_pk_bf16_f32 v13, v18, v19
	s_nop 0
	v_permlane32_swap_b32_e32 v10, v12
	v_permlane32_swap_b32_e32 v11, v13
	global_store_dwordx4 v[32:33], v[10:13], off offset:160
	s_nop 0
	ds_read_b128 v[10:13], v62 offset:384
	s_nop 0
	ds_read_b128 v[14:17], v62 offset:416
	s_waitcnt lgkmcnt(1)
	v_pk_mul_f32 v[8:9], v[8:9], v[10:11]
	v_pk_mul_f32 v[6:7], v[6:7], v[12:13]
	s_waitcnt lgkmcnt(0)
	v_pk_mul_f32 v[4:5], v[4:5], v[14:15]
	v_pk_mul_f32 v[10:11], v[2:3], v[16:17]
	v_cvt_pk_bf16_f32 v2, v8, v9
	v_cvt_pk_bf16_f32 v3, v6, v7
	v_cvt_pk_bf16_f32 v4, v4, v5
	v_cvt_pk_bf16_f32 v5, v10, v11
	s_nop 0
	v_permlane32_swap_b32_e32 v2, v4
	v_permlane32_swap_b32_e32 v3, v5
	global_store_dwordx4 v[32:33], v[2:5], off offset:192
	s_nop 0
	ds_read_b128 v[2:5], v62 offset:448
	s_nop 0
	ds_read_b128 v[6:9], v62 offset:480
	v_pk_mul_f32 v[10:11], v[58:59], v[34:35] op_sel_hi:[1,0]
	v_pk_mul_f32 v[12:13], v[64:65], v[34:35] op_sel_hi:[1,0]
	v_pk_mul_f32 v[14:15], v[60:61], v[34:35] op_sel_hi:[1,0]
	s_waitcnt lgkmcnt(1)
	v_pk_mul_f32 v[0:1], v[0:1], v[2:3]
	v_pk_mul_f32 v[2:3], v[10:11], v[4:5]
	s_waitcnt lgkmcnt(0)
	v_pk_mul_f32 v[4:5], v[12:13], v[6:7]
	v_pk_mul_f32 v[6:7], v[14:15], v[8:9]
	v_cvt_pk_bf16_f32 v0, v0, v1
	v_cvt_pk_bf16_f32 v1, v2, v3
	v_cvt_pk_bf16_f32 v2, v4, v5
	v_cvt_pk_bf16_f32 v3, v6, v7
	s_nop 0
	v_permlane32_swap_b32_e32 v0, v2
	v_permlane32_swap_b32_e32 v1, v3
	global_store_dwordx4 v[32:33], v[0:3], off offset:224
	s_branch .LBB0_256
